# RWKV scan step stream hand-scheduled: fully unrolled 32-step chunk, DPP wait states filled with v*kd products, next step LDS reads issued a full step ahead, no s_nop padding or loop overhead
# speedup vs baseline: 1.0219x; 1.0219x over previous
.LBB0_452:
	s_and_b32 s22, s12, 1
	s_mul_i32 s78, s22, 0xb200
	v_lshl_add_u32 v147, v79, 4, s78
	v_lshl_add_u32 v148, v113, 2, s78
	v_mov_b32_e32 v149, s78
	v_lshrrev_b32_e32 v119, 2, v79
	ds_read_b128 v[32:35], v147 offset:768
	ds_read_b128 v[36:39], v147 offset:1024
	ds_read_b128 v[24:27], v147 offset:256
	ds_read_b64 v[60:61], v148 offset:1280
	ds_read_b128 v[28:31], v147 offset:512
	ds_read_b128 v[20:23], v147 offset:0
	ds_read_b64 v[64:65], v149 offset:1408
	s_waitcnt vmcnt(0)
	s_waitcnt lgkmcnt(0)
	ds_read_b128 v[52:55], v147 offset:2192
	ds_read_b128 v[56:59], v147 offset:2448
	ds_read_b128 v[44:47], v147 offset:1680
	ds_read_b64 v[62:63], v148 offset:2704
	ds_read_b128 v[48:51], v147 offset:1936
	ds_read_b128 v[40:43], v147 offset:1424
	ds_read_b64 v[66:67], v149 offset:2832
	v_mul_f32_e32 v120, v12, v32
	v_mul_f32_e32 v121, v16, v32
	v_mul_f32_e32 v122, v12, v36
	v_mul_f32_e32 v123, v16, v36
	v_fmac_f32_e32 v120, v13, v33
	v_fmac_f32_e32 v121, v17, v33
	v_fmac_f32_e32 v122, v13, v37
	v_fmac_f32_e32 v123, v17, v37
	v_fmac_f32_e32 v120, v14, v34
	v_fmac_f32_e32 v121, v18, v34
	v_fmac_f32_e32 v122, v14, v38
	v_fmac_f32_e32 v123, v18, v38
	v_fmac_f32_e32 v120, v15, v35
	v_fmac_f32_e32 v121, v19, v35
	v_fmac_f32_e32 v122, v15, v39
	v_fmac_f32_e32 v123, v19, v39
	v_cndmask_b32_e64 v124, v120, v121, s[42:43]
	v_cndmask_b32_e64 v126, v122, v123, s[42:43]
	v_cndmask_b32_e64 v125, v121, v120, s[42:43]
	v_cndmask_b32_e64 v127, v123, v122, s[42:43]
	v_add_f32_dpp v124, v124, v125 quad_perm:[1,0,3,2] row_mask:0xf bank_mask:0xf bound_ctrl:1
	v_add_f32_dpp v126, v126, v127 quad_perm:[1,0,3,2] row_mask:0xf bank_mask:0xf bound_ctrl:1
	v_cndmask_b32_e64 v128, v124, v126, s[44:45]
	v_cndmask_b32_e64 v129, v126, v124, s[44:45]
	v_pk_mul_f32 v[136:137], v[24:25], v[60:61] op_sel_hi:[1,0]
	v_add_f32_dpp v130, v128, v129 quad_perm:[2,3,0,1] row_mask:0xf bank_mask:0xf bound_ctrl:1
	v_pk_mul_f32 v[138:139], v[26:27], v[60:61] op_sel_hi:[1,0]
	v_pk_mul_f32 v[140:141], v[24:25], v[60:61] op_sel:[0,1]
	v_add_f32_dpp v130, v130, v130 row_ror:4 row_mask:0xf bank_mask:0xf bound_ctrl:1
	v_pk_mul_f32 v[142:143], v[26:27], v[60:61] op_sel:[0,1]
	v_cndmask_b32_e64 v145, v61, v60, s[42:43]
	v_add_f32_dpp v130, v130, v130 row_ror:8 row_mask:0xf bank_mask:0xf bound_ctrl:1
	s_nop 0
	v_cmp_eq_u32_e32 vcc, 0, v119
	v_mov_b32_dpp v132, v130 quad_perm:[0,0,0,0] row_mask:0xf bank_mask:0xf bound_ctrl:1
	v_mov_b32_dpp v134, v130 quad_perm:[1,1,1,1] row_mask:0xf bank_mask:0xf bound_ctrl:1
	v_pk_fma_f32 v[136:137], v[28:29], v[132:133], v[136:137] op_sel_hi:[1,0,1]
	v_pk_fma_f32 v[138:139], v[30:31], v[132:133], v[138:139] op_sel_hi:[1,0,1]
	v_pk_fma_f32 v[140:141], v[28:29], v[134:135], v[140:141] op_sel_hi:[1,0,1]
	v_pk_fma_f32 v[142:143], v[30:31], v[134:135], v[142:143] op_sel_hi:[1,0,1]
	v_cndmask_b32_e64 v144, v134, v132, s[42:43]
	v_pk_fma_f32 v[12:13], v[12:13], v[20:21], v[136:137]
	v_pk_fma_f32 v[14:15], v[14:15], v[22:23], v[138:139]
	v_fma_f32 v146, v145, v65, v130
	v_pk_fma_f32 v[16:17], v[16:17], v[20:21], v[140:141]
	v_pk_fma_f32 v[18:19], v[18:19], v[22:23], v[142:143]
	v_fmac_f32_e32 v146, v144, v64
	s_waitcnt lgkmcnt(0)
	ds_read_b128 v[32:35], v147 offset:3616
	ds_read_b128 v[36:39], v147 offset:3872
	ds_read_b128 v[24:27], v147 offset:3104
	ds_read_b64 v[60:61], v148 offset:4128
	ds_read_b128 v[28:31], v147 offset:3360
	ds_read_b128 v[20:23], v147 offset:2848
	ds_read_b64 v[64:65], v149 offset:4256
	v_mul_f32_e32 v120, v12, v52
	v_mul_f32_e32 v121, v16, v52
	v_mul_f32_e32 v122, v12, v56
	v_mul_f32_e32 v123, v16, v56
	v_fmac_f32_e32 v120, v13, v53
	v_fmac_f32_e32 v121, v17, v53
	v_fmac_f32_e32 v122, v13, v57
	v_fmac_f32_e32 v123, v17, v57
	v_fmac_f32_e32 v120, v14, v54
	v_fmac_f32_e32 v121, v18, v54
	v_fmac_f32_e32 v122, v14, v58
	v_fmac_f32_e32 v123, v18, v58
	v_fmac_f32_e32 v120, v15, v55
	v_fmac_f32_e32 v121, v19, v55
	v_fmac_f32_e32 v122, v15, v59
	v_fmac_f32_e32 v123, v19, v59
	v_cndmask_b32_e64 v124, v120, v121, s[42:43]
	v_cndmask_b32_e64 v126, v122, v123, s[42:43]
	v_cndmask_b32_e64 v125, v121, v120, s[42:43]
	v_cndmask_b32_e64 v127, v123, v122, s[42:43]
	v_add_f32_dpp v124, v124, v125 quad_perm:[1,0,3,2] row_mask:0xf bank_mask:0xf bound_ctrl:1
	v_add_f32_dpp v126, v126, v127 quad_perm:[1,0,3,2] row_mask:0xf bank_mask:0xf bound_ctrl:1
	v_cndmask_b32_e64 v128, v124, v126, s[44:45]
	v_cndmask_b32_e64 v129, v126, v124, s[44:45]
	v_pk_mul_f32 v[136:137], v[44:45], v[62:63] op_sel_hi:[1,0]
	v_add_f32_dpp v130, v128, v129 quad_perm:[2,3,0,1] row_mask:0xf bank_mask:0xf bound_ctrl:1
	v_pk_mul_f32 v[138:139], v[46:47], v[62:63] op_sel_hi:[1,0]
	v_pk_mul_f32 v[140:141], v[44:45], v[62:63] op_sel:[0,1]
	v_add_f32_dpp v130, v130, v130 row_ror:4 row_mask:0xf bank_mask:0xf bound_ctrl:1
	v_pk_mul_f32 v[142:143], v[46:47], v[62:63] op_sel:[0,1]
	v_cndmask_b32_e64 v145, v63, v62, s[42:43]
	v_add_f32_dpp v130, v130, v130 row_ror:8 row_mask:0xf bank_mask:0xf bound_ctrl:1
	v_cndmask_b32_e32 v0, v0, v146, vcc
	s_nop 0
	v_mov_b32_dpp v132, v130 quad_perm:[0,0,0,0] row_mask:0xf bank_mask:0xf bound_ctrl:1
	v_mov_b32_dpp v134, v130 quad_perm:[1,1,1,1] row_mask:0xf bank_mask:0xf bound_ctrl:1
	v_pk_fma_f32 v[136:137], v[48:49], v[132:133], v[136:137] op_sel_hi:[1,0,1]
	v_pk_fma_f32 v[138:139], v[50:51], v[132:133], v[138:139] op_sel_hi:[1,0,1]
	v_pk_fma_f32 v[140:141], v[48:49], v[134:135], v[140:141] op_sel_hi:[1,0,1]
	v_pk_fma_f32 v[142:143], v[50:51], v[134:135], v[142:143] op_sel_hi:[1,0,1]
	v_cndmask_b32_e64 v144, v134, v132, s[42:43]
	v_pk_fma_f32 v[12:13], v[12:13], v[40:41], v[136:137]
	v_pk_fma_f32 v[14:15], v[14:15], v[42:43], v[138:139]
	v_fma_f32 v150, v145, v67, v130
	v_pk_fma_f32 v[16:17], v[16:17], v[40:41], v[140:141]
	v_pk_fma_f32 v[18:19], v[18:19], v[42:43], v[142:143]
	v_fmac_f32_e32 v150, v144, v66
	s_waitcnt lgkmcnt(0)
	ds_read_b128 v[52:55], v147 offset:5040
	ds_read_b128 v[56:59], v147 offset:5296
	ds_read_b128 v[44:47], v147 offset:4528
	ds_read_b64 v[62:63], v148 offset:5552
	ds_read_b128 v[48:51], v147 offset:4784
	ds_read_b128 v[40:43], v147 offset:4272
	ds_read_b64 v[66:67], v149 offset:5680
	v_mul_f32_e32 v120, v12, v32
	v_mul_f32_e32 v121, v16, v32
	v_mul_f32_e32 v122, v12, v36
	v_mul_f32_e32 v123, v16, v36
	v_fmac_f32_e32 v120, v13, v33
	v_fmac_f32_e32 v121, v17, v33
	v_fmac_f32_e32 v122, v13, v37
	v_fmac_f32_e32 v123, v17, v37
	v_fmac_f32_e32 v120, v14, v34
	v_fmac_f32_e32 v121, v18, v34
	v_fmac_f32_e32 v122, v14, v38
	v_fmac_f32_e32 v123, v18, v38
	v_fmac_f32_e32 v120, v15, v35
	v_fmac_f32_e32 v121, v19, v35
	v_fmac_f32_e32 v122, v15, v39
	v_fmac_f32_e32 v123, v19, v39
	v_cndmask_b32_e64 v124, v120, v121, s[42:43]
	v_cndmask_b32_e64 v126, v122, v123, s[42:43]
	v_cndmask_b32_e64 v125, v121, v120, s[42:43]
	v_cndmask_b32_e64 v127, v123, v122, s[42:43]
	v_add_f32_dpp v124, v124, v125 quad_perm:[1,0,3,2] row_mask:0xf bank_mask:0xf bound_ctrl:1
	v_add_f32_dpp v126, v126, v127 quad_perm:[1,0,3,2] row_mask:0xf bank_mask:0xf bound_ctrl:1
	v_cndmask_b32_e64 v128, v124, v126, s[44:45]
	v_cndmask_b32_e64 v129, v126, v124, s[44:45]
	v_pk_mul_f32 v[136:137], v[24:25], v[60:61] op_sel_hi:[1,0]
	v_add_f32_dpp v130, v128, v129 quad_perm:[2,3,0,1] row_mask:0xf bank_mask:0xf bound_ctrl:1
	v_pk_mul_f32 v[138:139], v[26:27], v[60:61] op_sel_hi:[1,0]
	v_pk_mul_f32 v[140:141], v[24:25], v[60:61] op_sel:[0,1]
	v_add_f32_dpp v130, v130, v130 row_ror:4 row_mask:0xf bank_mask:0xf bound_ctrl:1
	v_pk_mul_f32 v[142:143], v[26:27], v[60:61] op_sel:[0,1]
	v_cndmask_b32_e64 v145, v61, v60, s[42:43]
	v_add_f32_dpp v130, v130, v130 row_ror:8 row_mask:0xf bank_mask:0xf bound_ctrl:1
	v_cndmask_b32_e32 v1, v1, v150, vcc
	s_nop 0
	v_mov_b32_dpp v132, v130 quad_perm:[0,0,0,0] row_mask:0xf bank_mask:0xf bound_ctrl:1
	v_mov_b32_dpp v134, v130 quad_perm:[1,1,1,1] row_mask:0xf bank_mask:0xf bound_ctrl:1
	v_pk_fma_f32 v[136:137], v[28:29], v[132:133], v[136:137] op_sel_hi:[1,0,1]
	v_pk_fma_f32 v[138:139], v[30:31], v[132:133], v[138:139] op_sel_hi:[1,0,1]
	v_pk_fma_f32 v[140:141], v[28:29], v[134:135], v[140:141] op_sel_hi:[1,0,1]
	v_pk_fma_f32 v[142:143], v[30:31], v[134:135], v[142:143] op_sel_hi:[1,0,1]
	v_cndmask_b32_e64 v144, v134, v132, s[42:43]
	v_pk_fma_f32 v[12:13], v[12:13], v[20:21], v[136:137]
	v_pk_fma_f32 v[14:15], v[14:15], v[22:23], v[138:139]
	v_fma_f32 v146, v145, v65, v130
	v_pk_fma_f32 v[16:17], v[16:17], v[20:21], v[140:141]
	v_pk_fma_f32 v[18:19], v[18:19], v[22:23], v[142:143]
	v_fmac_f32_e32 v146, v144, v64
	s_waitcnt lgkmcnt(0)
	ds_read_b128 v[32:35], v147 offset:6464
	ds_read_b128 v[36:39], v147 offset:6720
	ds_read_b128 v[24:27], v147 offset:5952
	ds_read_b64 v[60:61], v148 offset:6976
	ds_read_b128 v[28:31], v147 offset:6208
	ds_read_b128 v[20:23], v147 offset:5696
	ds_read_b64 v[64:65], v149 offset:7104
	v_mul_f32_e32 v120, v12, v52
	v_mul_f32_e32 v121, v16, v52
	v_mul_f32_e32 v122, v12, v56
	v_mul_f32_e32 v123, v16, v56
	v_fmac_f32_e32 v120, v13, v53
	v_fmac_f32_e32 v121, v17, v53
	v_fmac_f32_e32 v122, v13, v57
	v_fmac_f32_e32 v123, v17, v57
	v_fmac_f32_e32 v120, v14, v54
	v_fmac_f32_e32 v121, v18, v54
	v_fmac_f32_e32 v122, v14, v58
	v_fmac_f32_e32 v123, v18, v58
	v_fmac_f32_e32 v120, v15, v55
	v_fmac_f32_e32 v121, v19, v55
	v_fmac_f32_e32 v122, v15, v59
	v_fmac_f32_e32 v123, v19, v59
	v_cndmask_b32_e64 v124, v120, v121, s[42:43]
	v_cndmask_b32_e64 v126, v122, v123, s[42:43]
	v_cndmask_b32_e64 v125, v121, v120, s[42:43]
	v_cndmask_b32_e64 v127, v123, v122, s[42:43]
	v_add_f32_dpp v124, v124, v125 quad_perm:[1,0,3,2] row_mask:0xf bank_mask:0xf bound_ctrl:1
	v_add_f32_dpp v126, v126, v127 quad_perm:[1,0,3,2] row_mask:0xf bank_mask:0xf bound_ctrl:1
	v_cndmask_b32_e64 v128, v124, v126, s[44:45]
	v_cndmask_b32_e64 v129, v126, v124, s[44:45]
	v_pk_mul_f32 v[136:137], v[44:45], v[62:63] op_sel_hi:[1,0]
	v_add_f32_dpp v130, v128, v129 quad_perm:[2,3,0,1] row_mask:0xf bank_mask:0xf bound_ctrl:1
	v_pk_mul_f32 v[138:139], v[46:47], v[62:63] op_sel_hi:[1,0]
	v_pk_mul_f32 v[140:141], v[44:45], v[62:63] op_sel:[0,1]
	v_add_f32_dpp v130, v130, v130 row_ror:4 row_mask:0xf bank_mask:0xf bound_ctrl:1
	v_pk_mul_f32 v[142:143], v[46:47], v[62:63] op_sel:[0,1]
	v_cndmask_b32_e64 v145, v63, v62, s[42:43]
	v_add_f32_dpp v130, v130, v130 row_ror:8 row_mask:0xf bank_mask:0xf bound_ctrl:1
	v_cndmask_b32_e32 v2, v2, v146, vcc
	s_nop 0
	v_mov_b32_dpp v132, v130 quad_perm:[0,0,0,0] row_mask:0xf bank_mask:0xf bound_ctrl:1
	v_mov_b32_dpp v134, v130 quad_perm:[1,1,1,1] row_mask:0xf bank_mask:0xf bound_ctrl:1
	v_pk_fma_f32 v[136:137], v[48:49], v[132:133], v[136:137] op_sel_hi:[1,0,1]
	v_pk_fma_f32 v[138:139], v[50:51], v[132:133], v[138:139] op_sel_hi:[1,0,1]
	v_pk_fma_f32 v[140:141], v[48:49], v[134:135], v[140:141] op_sel_hi:[1,0,1]
	v_pk_fma_f32 v[142:143], v[50:51], v[134:135], v[142:143] op_sel_hi:[1,0,1]
	v_cndmask_b32_e64 v144, v134, v132, s[42:43]
	v_pk_fma_f32 v[12:13], v[12:13], v[40:41], v[136:137]
	v_pk_fma_f32 v[14:15], v[14:15], v[42:43], v[138:139]
	v_fma_f32 v150, v145, v67, v130
	v_pk_fma_f32 v[16:17], v[16:17], v[40:41], v[140:141]
	v_pk_fma_f32 v[18:19], v[18:19], v[42:43], v[142:143]
	v_fmac_f32_e32 v150, v144, v66
	s_waitcnt lgkmcnt(0)
	ds_read_b128 v[52:55], v147 offset:7888
	ds_read_b128 v[56:59], v147 offset:8144
	ds_read_b128 v[44:47], v147 offset:7376
	ds_read_b64 v[62:63], v148 offset:8400
	ds_read_b128 v[48:51], v147 offset:7632
	ds_read_b128 v[40:43], v147 offset:7120
	ds_read_b64 v[66:67], v149 offset:8528
	v_mul_f32_e32 v120, v12, v32
	v_mul_f32_e32 v121, v16, v32
	v_mul_f32_e32 v122, v12, v36
	v_mul_f32_e32 v123, v16, v36
	v_fmac_f32_e32 v120, v13, v33
	v_fmac_f32_e32 v121, v17, v33
	v_fmac_f32_e32 v122, v13, v37
	v_fmac_f32_e32 v123, v17, v37
	v_fmac_f32_e32 v120, v14, v34
	v_fmac_f32_e32 v121, v18, v34
	v_fmac_f32_e32 v122, v14, v38
	v_fmac_f32_e32 v123, v18, v38
	v_fmac_f32_e32 v120, v15, v35
	v_fmac_f32_e32 v121, v19, v35
	v_fmac_f32_e32 v122, v15, v39
	v_fmac_f32_e32 v123, v19, v39
	v_cndmask_b32_e64 v124, v120, v121, s[42:43]
	v_cndmask_b32_e64 v126, v122, v123, s[42:43]
	v_cndmask_b32_e64 v125, v121, v120, s[42:43]
	v_cndmask_b32_e64 v127, v123, v122, s[42:43]
	v_add_f32_dpp v124, v124, v125 quad_perm:[1,0,3,2] row_mask:0xf bank_mask:0xf bound_ctrl:1
	v_add_f32_dpp v126, v126, v127 quad_perm:[1,0,3,2] row_mask:0xf bank_mask:0xf bound_ctrl:1
	v_cndmask_b32_e64 v128, v124, v126, s[44:45]
	v_cndmask_b32_e64 v129, v126, v124, s[44:45]
	v_pk_mul_f32 v[136:137], v[24:25], v[60:61] op_sel_hi:[1,0]
	v_add_f32_dpp v130, v128, v129 quad_perm:[2,3,0,1] row_mask:0xf bank_mask:0xf bound_ctrl:1
	v_pk_mul_f32 v[138:139], v[26:27], v[60:61] op_sel_hi:[1,0]
	v_pk_mul_f32 v[140:141], v[24:25], v[60:61] op_sel:[0,1]
	v_add_f32_dpp v130, v130, v130 row_ror:4 row_mask:0xf bank_mask:0xf bound_ctrl:1
	v_pk_mul_f32 v[142:143], v[26:27], v[60:61] op_sel:[0,1]
	v_cndmask_b32_e64 v145, v61, v60, s[42:43]
	v_add_f32_dpp v130, v130, v130 row_ror:8 row_mask:0xf bank_mask:0xf bound_ctrl:1
	v_cndmask_b32_e32 v3, v3, v150, vcc
	v_cmp_eq_u32_e32 vcc, 1, v119
	v_mov_b32_dpp v132, v130 quad_perm:[0,0,0,0] row_mask:0xf bank_mask:0xf bound_ctrl:1
	v_mov_b32_dpp v134, v130 quad_perm:[1,1,1,1] row_mask:0xf bank_mask:0xf bound_ctrl:1
	v_pk_fma_f32 v[136:137], v[28:29], v[132:133], v[136:137] op_sel_hi:[1,0,1]
	v_pk_fma_f32 v[138:139], v[30:31], v[132:133], v[138:139] op_sel_hi:[1,0,1]
	v_pk_fma_f32 v[140:141], v[28:29], v[134:135], v[140:141] op_sel_hi:[1,0,1]
	v_pk_fma_f32 v[142:143], v[30:31], v[134:135], v[142:143] op_sel_hi:[1,0,1]
	v_cndmask_b32_e64 v144, v134, v132, s[42:43]
	v_pk_fma_f32 v[12:13], v[12:13], v[20:21], v[136:137]
	v_pk_fma_f32 v[14:15], v[14:15], v[22:23], v[138:139]
	v_fma_f32 v146, v145, v65, v130
	v_pk_fma_f32 v[16:17], v[16:17], v[20:21], v[140:141]
	v_pk_fma_f32 v[18:19], v[18:19], v[22:23], v[142:143]
	v_fmac_f32_e32 v146, v144, v64
	s_waitcnt lgkmcnt(0)
	ds_read_b128 v[32:35], v147 offset:9312
	ds_read_b128 v[36:39], v147 offset:9568
	ds_read_b128 v[24:27], v147 offset:8800
	ds_read_b64 v[60:61], v148 offset:9824
	ds_read_b128 v[28:31], v147 offset:9056
	ds_read_b128 v[20:23], v147 offset:8544
	ds_read_b64 v[64:65], v149 offset:9952
	v_mul_f32_e32 v120, v12, v52
	v_mul_f32_e32 v121, v16, v52
	v_mul_f32_e32 v122, v12, v56
	v_mul_f32_e32 v123, v16, v56
	v_fmac_f32_e32 v120, v13, v53
	v_fmac_f32_e32 v121, v17, v53
	v_fmac_f32_e32 v122, v13, v57
	v_fmac_f32_e32 v123, v17, v57
	v_fmac_f32_e32 v120, v14, v54
	v_fmac_f32_e32 v121, v18, v54
	v_fmac_f32_e32 v122, v14, v58
	v_fmac_f32_e32 v123, v18, v58
	v_fmac_f32_e32 v120, v15, v55
	v_fmac_f32_e32 v121, v19, v55
	v_fmac_f32_e32 v122, v15, v59
	v_fmac_f32_e32 v123, v19, v59
	v_cndmask_b32_e64 v124, v120, v121, s[42:43]
	v_cndmask_b32_e64 v126, v122, v123, s[42:43]
	v_cndmask_b32_e64 v125, v121, v120, s[42:43]
	v_cndmask_b32_e64 v127, v123, v122, s[42:43]
	v_add_f32_dpp v124, v124, v125 quad_perm:[1,0,3,2] row_mask:0xf bank_mask:0xf bound_ctrl:1
	v_add_f32_dpp v126, v126, v127 quad_perm:[1,0,3,2] row_mask:0xf bank_mask:0xf bound_ctrl:1
	v_cndmask_b32_e64 v128, v124, v126, s[44:45]
	v_cndmask_b32_e64 v129, v126, v124, s[44:45]
	v_pk_mul_f32 v[136:137], v[44:45], v[62:63] op_sel_hi:[1,0]
	v_add_f32_dpp v130, v128, v129 quad_perm:[2,3,0,1] row_mask:0xf bank_mask:0xf bound_ctrl:1
	v_pk_mul_f32 v[138:139], v[46:47], v[62:63] op_sel_hi:[1,0]
	v_pk_mul_f32 v[140:141], v[44:45], v[62:63] op_sel:[0,1]
	v_add_f32_dpp v130, v130, v130 row_ror:4 row_mask:0xf bank_mask:0xf bound_ctrl:1
	v_pk_mul_f32 v[142:143], v[46:47], v[62:63] op_sel:[0,1]
	v_cndmask_b32_e64 v145, v63, v62, s[42:43]
	v_add_f32_dpp v130, v130, v130 row_ror:8 row_mask:0xf bank_mask:0xf bound_ctrl:1
	v_cndmask_b32_e32 v0, v0, v146, vcc
	s_nop 0
	v_mov_b32_dpp v132, v130 quad_perm:[0,0,0,0] row_mask:0xf bank_mask:0xf bound_ctrl:1
	v_mov_b32_dpp v134, v130 quad_perm:[1,1,1,1] row_mask:0xf bank_mask:0xf bound_ctrl:1
	v_pk_fma_f32 v[136:137], v[48:49], v[132:133], v[136:137] op_sel_hi:[1,0,1]
	v_pk_fma_f32 v[138:139], v[50:51], v[132:133], v[138:139] op_sel_hi:[1,0,1]
	v_pk_fma_f32 v[140:141], v[48:49], v[134:135], v[140:141] op_sel_hi:[1,0,1]
	v_pk_fma_f32 v[142:143], v[50:51], v[134:135], v[142:143] op_sel_hi:[1,0,1]
	v_cndmask_b32_e64 v144, v134, v132, s[42:43]
	v_pk_fma_f32 v[12:13], v[12:13], v[40:41], v[136:137]
	v_pk_fma_f32 v[14:15], v[14:15], v[42:43], v[138:139]
	v_fma_f32 v150, v145, v67, v130
	v_pk_fma_f32 v[16:17], v[16:17], v[40:41], v[140:141]
	v_pk_fma_f32 v[18:19], v[18:19], v[42:43], v[142:143]
	v_fmac_f32_e32 v150, v144, v66
	s_waitcnt lgkmcnt(0)
	ds_read_b128 v[52:55], v147 offset:10736
	ds_read_b128 v[56:59], v147 offset:10992
	ds_read_b128 v[44:47], v147 offset:10224
	ds_read_b64 v[62:63], v148 offset:11248
	ds_read_b128 v[48:51], v147 offset:10480
	ds_read_b128 v[40:43], v147 offset:9968
	ds_read_b64 v[66:67], v149 offset:11376
	v_mul_f32_e32 v120, v12, v32
	v_mul_f32_e32 v121, v16, v32
	v_mul_f32_e32 v122, v12, v36
	v_mul_f32_e32 v123, v16, v36
	v_fmac_f32_e32 v120, v13, v33
	v_fmac_f32_e32 v121, v17, v33
	v_fmac_f32_e32 v122, v13, v37
	v_fmac_f32_e32 v123, v17, v37
	v_fmac_f32_e32 v120, v14, v34
	v_fmac_f32_e32 v121, v18, v34
	v_fmac_f32_e32 v122, v14, v38
	v_fmac_f32_e32 v123, v18, v38
	v_fmac_f32_e32 v120, v15, v35
	v_fmac_f32_e32 v121, v19, v35
	v_fmac_f32_e32 v122, v15, v39
	v_fmac_f32_e32 v123, v19, v39
	v_cndmask_b32_e64 v124, v120, v121, s[42:43]
	v_cndmask_b32_e64 v126, v122, v123, s[42:43]
	v_cndmask_b32_e64 v125, v121, v120, s[42:43]
	v_cndmask_b32_e64 v127, v123, v122, s[42:43]
	v_add_f32_dpp v124, v124, v125 quad_perm:[1,0,3,2] row_mask:0xf bank_mask:0xf bound_ctrl:1
	v_add_f32_dpp v126, v126, v127 quad_perm:[1,0,3,2] row_mask:0xf bank_mask:0xf bound_ctrl:1
	v_cndmask_b32_e64 v128, v124, v126, s[44:45]
	v_cndmask_b32_e64 v129, v126, v124, s[44:45]
	v_pk_mul_f32 v[136:137], v[24:25], v[60:61] op_sel_hi:[1,0]
	v_add_f32_dpp v130, v128, v129 quad_perm:[2,3,0,1] row_mask:0xf bank_mask:0xf bound_ctrl:1
	v_pk_mul_f32 v[138:139], v[26:27], v[60:61] op_sel_hi:[1,0]
	v_pk_mul_f32 v[140:141], v[24:25], v[60:61] op_sel:[0,1]
	v_add_f32_dpp v130, v130, v130 row_ror:4 row_mask:0xf bank_mask:0xf bound_ctrl:1
	v_pk_mul_f32 v[142:143], v[26:27], v[60:61] op_sel:[0,1]
	v_cndmask_b32_e64 v145, v61, v60, s[42:43]
	v_add_f32_dpp v130, v130, v130 row_ror:8 row_mask:0xf bank_mask:0xf bound_ctrl:1
	v_cndmask_b32_e32 v1, v1, v150, vcc
	s_nop 0
	v_mov_b32_dpp v132, v130 quad_perm:[0,0,0,0] row_mask:0xf bank_mask:0xf bound_ctrl:1
	v_mov_b32_dpp v134, v130 quad_perm:[1,1,1,1] row_mask:0xf bank_mask:0xf bound_ctrl:1
	v_pk_fma_f32 v[136:137], v[28:29], v[132:133], v[136:137] op_sel_hi:[1,0,1]
	v_pk_fma_f32 v[138:139], v[30:31], v[132:133], v[138:139] op_sel_hi:[1,0,1]
	v_pk_fma_f32 v[140:141], v[28:29], v[134:135], v[140:141] op_sel_hi:[1,0,1]
	v_pk_fma_f32 v[142:143], v[30:31], v[134:135], v[142:143] op_sel_hi:[1,0,1]
	v_cndmask_b32_e64 v144, v134, v132, s[42:43]
	v_pk_fma_f32 v[12:13], v[12:13], v[20:21], v[136:137]
	v_pk_fma_f32 v[14:15], v[14:15], v[22:23], v[138:139]
	v_fma_f32 v146, v145, v65, v130
	v_pk_fma_f32 v[16:17], v[16:17], v[20:21], v[140:141]
	v_pk_fma_f32 v[18:19], v[18:19], v[22:23], v[142:143]
	v_fmac_f32_e32 v146, v144, v64
	s_waitcnt lgkmcnt(0)
	ds_read_b128 v[32:35], v147 offset:12160
	ds_read_b128 v[36:39], v147 offset:12416
	ds_read_b128 v[24:27], v147 offset:11648
	ds_read_b64 v[60:61], v148 offset:12672
	ds_read_b128 v[28:31], v147 offset:11904
	ds_read_b128 v[20:23], v147 offset:11392
	ds_read_b64 v[64:65], v149 offset:12800
	v_mul_f32_e32 v120, v12, v52
	v_mul_f32_e32 v121, v16, v52
	v_mul_f32_e32 v122, v12, v56
	v_mul_f32_e32 v123, v16, v56
	v_fmac_f32_e32 v120, v13, v53
	v_fmac_f32_e32 v121, v17, v53
	v_fmac_f32_e32 v122, v13, v57
	v_fmac_f32_e32 v123, v17, v57
	v_fmac_f32_e32 v120, v14, v54
	v_fmac_f32_e32 v121, v18, v54
	v_fmac_f32_e32 v122, v14, v58
	v_fmac_f32_e32 v123, v18, v58
	v_fmac_f32_e32 v120, v15, v55
	v_fmac_f32_e32 v121, v19, v55
	v_fmac_f32_e32 v122, v15, v59
	v_fmac_f32_e32 v123, v19, v59
	v_cndmask_b32_e64 v124, v120, v121, s[42:43]
	v_cndmask_b32_e64 v126, v122, v123, s[42:43]
	v_cndmask_b32_e64 v125, v121, v120, s[42:43]
	v_cndmask_b32_e64 v127, v123, v122, s[42:43]
	v_add_f32_dpp v124, v124, v125 quad_perm:[1,0,3,2] row_mask:0xf bank_mask:0xf bound_ctrl:1
	v_add_f32_dpp v126, v126, v127 quad_perm:[1,0,3,2] row_mask:0xf bank_mask:0xf bound_ctrl:1
	v_cndmask_b32_e64 v128, v124, v126, s[44:45]
	v_cndmask_b32_e64 v129, v126, v124, s[44:45]
	v_pk_mul_f32 v[136:137], v[44:45], v[62:63] op_sel_hi:[1,0]
	v_add_f32_dpp v130, v128, v129 quad_perm:[2,3,0,1] row_mask:0xf bank_mask:0xf bound_ctrl:1
	v_pk_mul_f32 v[138:139], v[46:47], v[62:63] op_sel_hi:[1,0]
	v_pk_mul_f32 v[140:141], v[44:45], v[62:63] op_sel:[0,1]
	v_add_f32_dpp v130, v130, v130 row_ror:4 row_mask:0xf bank_mask:0xf bound_ctrl:1
	v_pk_mul_f32 v[142:143], v[46:47], v[62:63] op_sel:[0,1]
	v_cndmask_b32_e64 v145, v63, v62, s[42:43]
	v_add_f32_dpp v130, v130, v130 row_ror:8 row_mask:0xf bank_mask:0xf bound_ctrl:1
	v_cndmask_b32_e32 v2, v2, v146, vcc
	s_nop 0
	v_mov_b32_dpp v132, v130 quad_perm:[0,0,0,0] row_mask:0xf bank_mask:0xf bound_ctrl:1
	v_mov_b32_dpp v134, v130 quad_perm:[1,1,1,1] row_mask:0xf bank_mask:0xf bound_ctrl:1
	v_pk_fma_f32 v[136:137], v[48:49], v[132:133], v[136:137] op_sel_hi:[1,0,1]
	v_pk_fma_f32 v[138:139], v[50:51], v[132:133], v[138:139] op_sel_hi:[1,0,1]
	v_pk_fma_f32 v[140:141], v[48:49], v[134:135], v[140:141] op_sel_hi:[1,0,1]
	v_pk_fma_f32 v[142:143], v[50:51], v[134:135], v[142:143] op_sel_hi:[1,0,1]
	v_cndmask_b32_e64 v144, v134, v132, s[42:43]
	v_pk_fma_f32 v[12:13], v[12:13], v[40:41], v[136:137]
	v_pk_fma_f32 v[14:15], v[14:15], v[42:43], v[138:139]
	v_fma_f32 v150, v145, v67, v130
	v_pk_fma_f32 v[16:17], v[16:17], v[40:41], v[140:141]
	v_pk_fma_f32 v[18:19], v[18:19], v[42:43], v[142:143]
	v_fmac_f32_e32 v150, v144, v66
	s_waitcnt lgkmcnt(0)
	ds_read_b128 v[52:55], v147 offset:13584
	ds_read_b128 v[56:59], v147 offset:13840
	ds_read_b128 v[44:47], v147 offset:13072
	ds_read_b64 v[62:63], v148 offset:14096
	ds_read_b128 v[48:51], v147 offset:13328
	ds_read_b128 v[40:43], v147 offset:12816
	ds_read_b64 v[66:67], v149 offset:14224
	v_mul_f32_e32 v120, v12, v32
	v_mul_f32_e32 v121, v16, v32
	v_mul_f32_e32 v122, v12, v36
	v_mul_f32_e32 v123, v16, v36
	v_fmac_f32_e32 v120, v13, v33
	v_fmac_f32_e32 v121, v17, v33
	v_fmac_f32_e32 v122, v13, v37
	v_fmac_f32_e32 v123, v17, v37
	v_fmac_f32_e32 v120, v14, v34
	v_fmac_f32_e32 v121, v18, v34
	v_fmac_f32_e32 v122, v14, v38
	v_fmac_f32_e32 v123, v18, v38
	v_fmac_f32_e32 v120, v15, v35
	v_fmac_f32_e32 v121, v19, v35
	v_fmac_f32_e32 v122, v15, v39
	v_fmac_f32_e32 v123, v19, v39
	v_cndmask_b32_e64 v124, v120, v121, s[42:43]
	v_cndmask_b32_e64 v126, v122, v123, s[42:43]
	v_cndmask_b32_e64 v125, v121, v120, s[42:43]
	v_cndmask_b32_e64 v127, v123, v122, s[42:43]
	v_add_f32_dpp v124, v124, v125 quad_perm:[1,0,3,2] row_mask:0xf bank_mask:0xf bound_ctrl:1
	v_add_f32_dpp v126, v126, v127 quad_perm:[1,0,3,2] row_mask:0xf bank_mask:0xf bound_ctrl:1
	v_cndmask_b32_e64 v128, v124, v126, s[44:45]
	v_cndmask_b32_e64 v129, v126, v124, s[44:45]
	v_pk_mul_f32 v[136:137], v[24:25], v[60:61] op_sel_hi:[1,0]
	v_add_f32_dpp v130, v128, v129 quad_perm:[2,3,0,1] row_mask:0xf bank_mask:0xf bound_ctrl:1
	v_pk_mul_f32 v[138:139], v[26:27], v[60:61] op_sel_hi:[1,0]
	v_pk_mul_f32 v[140:141], v[24:25], v[60:61] op_sel:[0,1]
	v_add_f32_dpp v130, v130, v130 row_ror:4 row_mask:0xf bank_mask:0xf bound_ctrl:1
	v_pk_mul_f32 v[142:143], v[26:27], v[60:61] op_sel:[0,1]
	v_cndmask_b32_e64 v145, v61, v60, s[42:43]
	v_add_f32_dpp v130, v130, v130 row_ror:8 row_mask:0xf bank_mask:0xf bound_ctrl:1
	v_cndmask_b32_e32 v3, v3, v150, vcc
	v_cmp_eq_u32_e32 vcc, 2, v119
	v_mov_b32_dpp v132, v130 quad_perm:[0,0,0,0] row_mask:0xf bank_mask:0xf bound_ctrl:1
	v_mov_b32_dpp v134, v130 quad_perm:[1,1,1,1] row_mask:0xf bank_mask:0xf bound_ctrl:1
	v_pk_fma_f32 v[136:137], v[28:29], v[132:133], v[136:137] op_sel_hi:[1,0,1]
	v_pk_fma_f32 v[138:139], v[30:31], v[132:133], v[138:139] op_sel_hi:[1,0,1]
	v_pk_fma_f32 v[140:141], v[28:29], v[134:135], v[140:141] op_sel_hi:[1,0,1]
	v_pk_fma_f32 v[142:143], v[30:31], v[134:135], v[142:143] op_sel_hi:[1,0,1]
	v_cndmask_b32_e64 v144, v134, v132, s[42:43]
	v_pk_fma_f32 v[12:13], v[12:13], v[20:21], v[136:137]
	v_pk_fma_f32 v[14:15], v[14:15], v[22:23], v[138:139]
	v_fma_f32 v146, v145, v65, v130
	v_pk_fma_f32 v[16:17], v[16:17], v[20:21], v[140:141]
	v_pk_fma_f32 v[18:19], v[18:19], v[22:23], v[142:143]
	v_fmac_f32_e32 v146, v144, v64
	s_waitcnt lgkmcnt(0)
	ds_read_b128 v[32:35], v147 offset:15008
	ds_read_b128 v[36:39], v147 offset:15264
	ds_read_b128 v[24:27], v147 offset:14496
	ds_read_b64 v[60:61], v148 offset:15520
	ds_read_b128 v[28:31], v147 offset:14752
	ds_read_b128 v[20:23], v147 offset:14240
	ds_read_b64 v[64:65], v149 offset:15648
	v_mul_f32_e32 v120, v12, v52
	v_mul_f32_e32 v121, v16, v52
	v_mul_f32_e32 v122, v12, v56
	v_mul_f32_e32 v123, v16, v56
	v_fmac_f32_e32 v120, v13, v53
	v_fmac_f32_e32 v121, v17, v53
	v_fmac_f32_e32 v122, v13, v57
	v_fmac_f32_e32 v123, v17, v57
	v_fmac_f32_e32 v120, v14, v54
	v_fmac_f32_e32 v121, v18, v54
	v_fmac_f32_e32 v122, v14, v58
	v_fmac_f32_e32 v123, v18, v58
	v_fmac_f32_e32 v120, v15, v55
	v_fmac_f32_e32 v121, v19, v55
	v_fmac_f32_e32 v122, v15, v59
	v_fmac_f32_e32 v123, v19, v59
	v_cndmask_b32_e64 v124, v120, v121, s[42:43]
	v_cndmask_b32_e64 v126, v122, v123, s[42:43]
	v_cndmask_b32_e64 v125, v121, v120, s[42:43]
	v_cndmask_b32_e64 v127, v123, v122, s[42:43]
	v_add_f32_dpp v124, v124, v125 quad_perm:[1,0,3,2] row_mask:0xf bank_mask:0xf bound_ctrl:1
	v_add_f32_dpp v126, v126, v127 quad_perm:[1,0,3,2] row_mask:0xf bank_mask:0xf bound_ctrl:1
	v_cndmask_b32_e64 v128, v124, v126, s[44:45]
	v_cndmask_b32_e64 v129, v126, v124, s[44:45]
	v_pk_mul_f32 v[136:137], v[44:45], v[62:63] op_sel_hi:[1,0]
	v_add_f32_dpp v130, v128, v129 quad_perm:[2,3,0,1] row_mask:0xf bank_mask:0xf bound_ctrl:1
	v_pk_mul_f32 v[138:139], v[46:47], v[62:63] op_sel_hi:[1,0]
	v_pk_mul_f32 v[140:141], v[44:45], v[62:63] op_sel:[0,1]
	v_add_f32_dpp v130, v130, v130 row_ror:4 row_mask:0xf bank_mask:0xf bound_ctrl:1
	v_pk_mul_f32 v[142:143], v[46:47], v[62:63] op_sel:[0,1]
	v_cndmask_b32_e64 v145, v63, v62, s[42:43]
	v_add_f32_dpp v130, v130, v130 row_ror:8 row_mask:0xf bank_mask:0xf bound_ctrl:1
	v_cndmask_b32_e32 v0, v0, v146, vcc
	s_nop 0
	v_mov_b32_dpp v132, v130 quad_perm:[0,0,0,0] row_mask:0xf bank_mask:0xf bound_ctrl:1
	v_mov_b32_dpp v134, v130 quad_perm:[1,1,1,1] row_mask:0xf bank_mask:0xf bound_ctrl:1
	v_pk_fma_f32 v[136:137], v[48:49], v[132:133], v[136:137] op_sel_hi:[1,0,1]
	v_pk_fma_f32 v[138:139], v[50:51], v[132:133], v[138:139] op_sel_hi:[1,0,1]
	v_pk_fma_f32 v[140:141], v[48:49], v[134:135], v[140:141] op_sel_hi:[1,0,1]
	v_pk_fma_f32 v[142:143], v[50:51], v[134:135], v[142:143] op_sel_hi:[1,0,1]
	v_cndmask_b32_e64 v144, v134, v132, s[42:43]
	v_pk_fma_f32 v[12:13], v[12:13], v[40:41], v[136:137]
	v_pk_fma_f32 v[14:15], v[14:15], v[42:43], v[138:139]
	v_fma_f32 v150, v145, v67, v130
	v_pk_fma_f32 v[16:17], v[16:17], v[40:41], v[140:141]
	v_pk_fma_f32 v[18:19], v[18:19], v[42:43], v[142:143]
	v_fmac_f32_e32 v150, v144, v66
	s_waitcnt lgkmcnt(0)
	ds_read_b128 v[52:55], v147 offset:16432
	ds_read_b128 v[56:59], v147 offset:16688
	ds_read_b128 v[44:47], v147 offset:15920
	ds_read_b64 v[62:63], v148 offset:16944
	ds_read_b128 v[48:51], v147 offset:16176
	ds_read_b128 v[40:43], v147 offset:15664
	ds_read_b64 v[66:67], v149 offset:17072
	v_mul_f32_e32 v120, v12, v32
	v_mul_f32_e32 v121, v16, v32
	v_mul_f32_e32 v122, v12, v36
	v_mul_f32_e32 v123, v16, v36
	v_fmac_f32_e32 v120, v13, v33
	v_fmac_f32_e32 v121, v17, v33
	v_fmac_f32_e32 v122, v13, v37
	v_fmac_f32_e32 v123, v17, v37
	v_fmac_f32_e32 v120, v14, v34
	v_fmac_f32_e32 v121, v18, v34
	v_fmac_f32_e32 v122, v14, v38
	v_fmac_f32_e32 v123, v18, v38
	v_fmac_f32_e32 v120, v15, v35
	v_fmac_f32_e32 v121, v19, v35
	v_fmac_f32_e32 v122, v15, v39
	v_fmac_f32_e32 v123, v19, v39
	v_cndmask_b32_e64 v124, v120, v121, s[42:43]
	v_cndmask_b32_e64 v126, v122, v123, s[42:43]
	v_cndmask_b32_e64 v125, v121, v120, s[42:43]
	v_cndmask_b32_e64 v127, v123, v122, s[42:43]
	v_add_f32_dpp v124, v124, v125 quad_perm:[1,0,3,2] row_mask:0xf bank_mask:0xf bound_ctrl:1
	v_add_f32_dpp v126, v126, v127 quad_perm:[1,0,3,2] row_mask:0xf bank_mask:0xf bound_ctrl:1
	v_cndmask_b32_e64 v128, v124, v126, s[44:45]
	v_cndmask_b32_e64 v129, v126, v124, s[44:45]
	v_pk_mul_f32 v[136:137], v[24:25], v[60:61] op_sel_hi:[1,0]
	v_add_f32_dpp v130, v128, v129 quad_perm:[2,3,0,1] row_mask:0xf bank_mask:0xf bound_ctrl:1
	v_pk_mul_f32 v[138:139], v[26:27], v[60:61] op_sel_hi:[1,0]
	v_pk_mul_f32 v[140:141], v[24:25], v[60:61] op_sel:[0,1]
	v_add_f32_dpp v130, v130, v130 row_ror:4 row_mask:0xf bank_mask:0xf bound_ctrl:1
	v_pk_mul_f32 v[142:143], v[26:27], v[60:61] op_sel:[0,1]
	v_cndmask_b32_e64 v145, v61, v60, s[42:43]
	v_add_f32_dpp v130, v130, v130 row_ror:8 row_mask:0xf bank_mask:0xf bound_ctrl:1
	v_cndmask_b32_e32 v1, v1, v150, vcc
	s_nop 0
	v_mov_b32_dpp v132, v130 quad_perm:[0,0,0,0] row_mask:0xf bank_mask:0xf bound_ctrl:1
	v_mov_b32_dpp v134, v130 quad_perm:[1,1,1,1] row_mask:0xf bank_mask:0xf bound_ctrl:1
	v_pk_fma_f32 v[136:137], v[28:29], v[132:133], v[136:137] op_sel_hi:[1,0,1]
	v_pk_fma_f32 v[138:139], v[30:31], v[132:133], v[138:139] op_sel_hi:[1,0,1]
	v_pk_fma_f32 v[140:141], v[28:29], v[134:135], v[140:141] op_sel_hi:[1,0,1]
	v_pk_fma_f32 v[142:143], v[30:31], v[134:135], v[142:143] op_sel_hi:[1,0,1]
	v_cndmask_b32_e64 v144, v134, v132, s[42:43]
	v_pk_fma_f32 v[12:13], v[12:13], v[20:21], v[136:137]
	v_pk_fma_f32 v[14:15], v[14:15], v[22:23], v[138:139]
	v_fma_f32 v146, v145, v65, v130
	v_pk_fma_f32 v[16:17], v[16:17], v[20:21], v[140:141]
	v_pk_fma_f32 v[18:19], v[18:19], v[22:23], v[142:143]
	v_fmac_f32_e32 v146, v144, v64
	s_waitcnt lgkmcnt(0)
	ds_read_b128 v[32:35], v147 offset:17856
	ds_read_b128 v[36:39], v147 offset:18112
	ds_read_b128 v[24:27], v147 offset:17344
	ds_read_b64 v[60:61], v148 offset:18368
	ds_read_b128 v[28:31], v147 offset:17600
	ds_read_b128 v[20:23], v147 offset:17088
	ds_read_b64 v[64:65], v149 offset:18496
	v_mul_f32_e32 v120, v12, v52
	v_mul_f32_e32 v121, v16, v52
	v_mul_f32_e32 v122, v12, v56
	v_mul_f32_e32 v123, v16, v56
	v_fmac_f32_e32 v120, v13, v53
	v_fmac_f32_e32 v121, v17, v53
	v_fmac_f32_e32 v122, v13, v57
	v_fmac_f32_e32 v123, v17, v57
	v_fmac_f32_e32 v120, v14, v54
	v_fmac_f32_e32 v121, v18, v54
	v_fmac_f32_e32 v122, v14, v58
	v_fmac_f32_e32 v123, v18, v58
	v_fmac_f32_e32 v120, v15, v55
	v_fmac_f32_e32 v121, v19, v55
	v_fmac_f32_e32 v122, v15, v59
	v_fmac_f32_e32 v123, v19, v59
	v_cndmask_b32_e64 v124, v120, v121, s[42:43]
	v_cndmask_b32_e64 v126, v122, v123, s[42:43]
	v_cndmask_b32_e64 v125, v121, v120, s[42:43]
	v_cndmask_b32_e64 v127, v123, v122, s[42:43]
	v_add_f32_dpp v124, v124, v125 quad_perm:[1,0,3,2] row_mask:0xf bank_mask:0xf bound_ctrl:1
	v_add_f32_dpp v126, v126, v127 quad_perm:[1,0,3,2] row_mask:0xf bank_mask:0xf bound_ctrl:1
	v_cndmask_b32_e64 v128, v124, v126, s[44:45]
	v_cndmask_b32_e64 v129, v126, v124, s[44:45]
	v_pk_mul_f32 v[136:137], v[44:45], v[62:63] op_sel_hi:[1,0]
	v_add_f32_dpp v130, v128, v129 quad_perm:[2,3,0,1] row_mask:0xf bank_mask:0xf bound_ctrl:1
	v_pk_mul_f32 v[138:139], v[46:47], v[62:63] op_sel_hi:[1,0]
	v_pk_mul_f32 v[140:141], v[44:45], v[62:63] op_sel:[0,1]
	v_add_f32_dpp v130, v130, v130 row_ror:4 row_mask:0xf bank_mask:0xf bound_ctrl:1
	v_pk_mul_f32 v[142:143], v[46:47], v[62:63] op_sel:[0,1]
	v_cndmask_b32_e64 v145, v63, v62, s[42:43]
	v_add_f32_dpp v130, v130, v130 row_ror:8 row_mask:0xf bank_mask:0xf bound_ctrl:1
	v_cndmask_b32_e32 v2, v2, v146, vcc
	s_nop 0
	v_mov_b32_dpp v132, v130 quad_perm:[0,0,0,0] row_mask:0xf bank_mask:0xf bound_ctrl:1
	v_mov_b32_dpp v134, v130 quad_perm:[1,1,1,1] row_mask:0xf bank_mask:0xf bound_ctrl:1
	v_pk_fma_f32 v[136:137], v[48:49], v[132:133], v[136:137] op_sel_hi:[1,0,1]
	v_pk_fma_f32 v[138:139], v[50:51], v[132:133], v[138:139] op_sel_hi:[1,0,1]
	v_pk_fma_f32 v[140:141], v[48:49], v[134:135], v[140:141] op_sel_hi:[1,0,1]
	v_pk_fma_f32 v[142:143], v[50:51], v[134:135], v[142:143] op_sel_hi:[1,0,1]
	v_cndmask_b32_e64 v144, v134, v132, s[42:43]
	v_pk_fma_f32 v[12:13], v[12:13], v[40:41], v[136:137]
	v_pk_fma_f32 v[14:15], v[14:15], v[42:43], v[138:139]
	v_fma_f32 v150, v145, v67, v130
	v_pk_fma_f32 v[16:17], v[16:17], v[40:41], v[140:141]
	v_pk_fma_f32 v[18:19], v[18:19], v[42:43], v[142:143]
	v_fmac_f32_e32 v150, v144, v66
	s_waitcnt lgkmcnt(0)
	ds_read_b128 v[52:55], v147 offset:19280
	ds_read_b128 v[56:59], v147 offset:19536
	ds_read_b128 v[44:47], v147 offset:18768
	ds_read_b64 v[62:63], v148 offset:19792
	ds_read_b128 v[48:51], v147 offset:19024
	ds_read_b128 v[40:43], v147 offset:18512
	ds_read_b64 v[66:67], v149 offset:19920
	v_mul_f32_e32 v120, v12, v32
	v_mul_f32_e32 v121, v16, v32
	v_mul_f32_e32 v122, v12, v36
	v_mul_f32_e32 v123, v16, v36
	v_fmac_f32_e32 v120, v13, v33
	v_fmac_f32_e32 v121, v17, v33
	v_fmac_f32_e32 v122, v13, v37
	v_fmac_f32_e32 v123, v17, v37
	v_fmac_f32_e32 v120, v14, v34
	v_fmac_f32_e32 v121, v18, v34
	v_fmac_f32_e32 v122, v14, v38
	v_fmac_f32_e32 v123, v18, v38
	v_fmac_f32_e32 v120, v15, v35
	v_fmac_f32_e32 v121, v19, v35
	v_fmac_f32_e32 v122, v15, v39
	v_fmac_f32_e32 v123, v19, v39
	v_cndmask_b32_e64 v124, v120, v121, s[42:43]
	v_cndmask_b32_e64 v126, v122, v123, s[42:43]
	v_cndmask_b32_e64 v125, v121, v120, s[42:43]
	v_cndmask_b32_e64 v127, v123, v122, s[42:43]
	v_add_f32_dpp v124, v124, v125 quad_perm:[1,0,3,2] row_mask:0xf bank_mask:0xf bound_ctrl:1
	v_add_f32_dpp v126, v126, v127 quad_perm:[1,0,3,2] row_mask:0xf bank_mask:0xf bound_ctrl:1
	v_cndmask_b32_e64 v128, v124, v126, s[44:45]
	v_cndmask_b32_e64 v129, v126, v124, s[44:45]
	v_pk_mul_f32 v[136:137], v[24:25], v[60:61] op_sel_hi:[1,0]
	v_add_f32_dpp v130, v128, v129 quad_perm:[2,3,0,1] row_mask:0xf bank_mask:0xf bound_ctrl:1
	v_pk_mul_f32 v[138:139], v[26:27], v[60:61] op_sel_hi:[1,0]
	v_pk_mul_f32 v[140:141], v[24:25], v[60:61] op_sel:[0,1]
	v_add_f32_dpp v130, v130, v130 row_ror:4 row_mask:0xf bank_mask:0xf bound_ctrl:1
	v_pk_mul_f32 v[142:143], v[26:27], v[60:61] op_sel:[0,1]
	v_cndmask_b32_e64 v145, v61, v60, s[42:43]
	v_add_f32_dpp v130, v130, v130 row_ror:8 row_mask:0xf bank_mask:0xf bound_ctrl:1
	v_cndmask_b32_e32 v3, v3, v150, vcc
	v_cmp_eq_u32_e32 vcc, 3, v119
	v_mov_b32_dpp v132, v130 quad_perm:[0,0,0,0] row_mask:0xf bank_mask:0xf bound_ctrl:1
	v_mov_b32_dpp v134, v130 quad_perm:[1,1,1,1] row_mask:0xf bank_mask:0xf bound_ctrl:1
	v_pk_fma_f32 v[136:137], v[28:29], v[132:133], v[136:137] op_sel_hi:[1,0,1]
	v_pk_fma_f32 v[138:139], v[30:31], v[132:133], v[138:139] op_sel_hi:[1,0,1]
	v_pk_fma_f32 v[140:141], v[28:29], v[134:135], v[140:141] op_sel_hi:[1,0,1]
	v_pk_fma_f32 v[142:143], v[30:31], v[134:135], v[142:143] op_sel_hi:[1,0,1]
	v_cndmask_b32_e64 v144, v134, v132, s[42:43]
	v_pk_fma_f32 v[12:13], v[12:13], v[20:21], v[136:137]
	v_pk_fma_f32 v[14:15], v[14:15], v[22:23], v[138:139]
	v_fma_f32 v146, v145, v65, v130
	v_pk_fma_f32 v[16:17], v[16:17], v[20:21], v[140:141]
	v_pk_fma_f32 v[18:19], v[18:19], v[22:23], v[142:143]
	v_fmac_f32_e32 v146, v144, v64
	s_waitcnt lgkmcnt(0)
	ds_read_b128 v[32:35], v147 offset:20704
	ds_read_b128 v[36:39], v147 offset:20960
	ds_read_b128 v[24:27], v147 offset:20192
	ds_read_b64 v[60:61], v148 offset:21216
	ds_read_b128 v[28:31], v147 offset:20448
	ds_read_b128 v[20:23], v147 offset:19936
	ds_read_b64 v[64:65], v149 offset:21344
	v_mul_f32_e32 v120, v12, v52
	v_mul_f32_e32 v121, v16, v52
	v_mul_f32_e32 v122, v12, v56
	v_mul_f32_e32 v123, v16, v56
	v_fmac_f32_e32 v120, v13, v53
	v_fmac_f32_e32 v121, v17, v53
	v_fmac_f32_e32 v122, v13, v57
	v_fmac_f32_e32 v123, v17, v57
	v_fmac_f32_e32 v120, v14, v54
	v_fmac_f32_e32 v121, v18, v54
	v_fmac_f32_e32 v122, v14, v58
	v_fmac_f32_e32 v123, v18, v58
	v_fmac_f32_e32 v120, v15, v55
	v_fmac_f32_e32 v121, v19, v55
	v_fmac_f32_e32 v122, v15, v59
	v_fmac_f32_e32 v123, v19, v59
	v_cndmask_b32_e64 v124, v120, v121, s[42:43]
	v_cndmask_b32_e64 v126, v122, v123, s[42:43]
	v_cndmask_b32_e64 v125, v121, v120, s[42:43]
	v_cndmask_b32_e64 v127, v123, v122, s[42:43]
	v_add_f32_dpp v124, v124, v125 quad_perm:[1,0,3,2] row_mask:0xf bank_mask:0xf bound_ctrl:1
	v_add_f32_dpp v126, v126, v127 quad_perm:[1,0,3,2] row_mask:0xf bank_mask:0xf bound_ctrl:1
	v_cndmask_b32_e64 v128, v124, v126, s[44:45]
	v_cndmask_b32_e64 v129, v126, v124, s[44:45]
	v_pk_mul_f32 v[136:137], v[44:45], v[62:63] op_sel_hi:[1,0]
	v_add_f32_dpp v130, v128, v129 quad_perm:[2,3,0,1] row_mask:0xf bank_mask:0xf bound_ctrl:1
	v_pk_mul_f32 v[138:139], v[46:47], v[62:63] op_sel_hi:[1,0]
	v_pk_mul_f32 v[140:141], v[44:45], v[62:63] op_sel:[0,1]
	v_add_f32_dpp v130, v130, v130 row_ror:4 row_mask:0xf bank_mask:0xf bound_ctrl:1
	v_pk_mul_f32 v[142:143], v[46:47], v[62:63] op_sel:[0,1]
	v_cndmask_b32_e64 v145, v63, v62, s[42:43]
	v_add_f32_dpp v130, v130, v130 row_ror:8 row_mask:0xf bank_mask:0xf bound_ctrl:1
	v_cndmask_b32_e32 v0, v0, v146, vcc
	s_nop 0
	v_mov_b32_dpp v132, v130 quad_perm:[0,0,0,0] row_mask:0xf bank_mask:0xf bound_ctrl:1
	v_mov_b32_dpp v134, v130 quad_perm:[1,1,1,1] row_mask:0xf bank_mask:0xf bound_ctrl:1
	v_pk_fma_f32 v[136:137], v[48:49], v[132:133], v[136:137] op_sel_hi:[1,0,1]
	v_pk_fma_f32 v[138:139], v[50:51], v[132:133], v[138:139] op_sel_hi:[1,0,1]
	v_pk_fma_f32 v[140:141], v[48:49], v[134:135], v[140:141] op_sel_hi:[1,0,1]
	v_pk_fma_f32 v[142:143], v[50:51], v[134:135], v[142:143] op_sel_hi:[1,0,1]
	v_cndmask_b32_e64 v144, v134, v132, s[42:43]
	v_pk_fma_f32 v[12:13], v[12:13], v[40:41], v[136:137]
	v_pk_fma_f32 v[14:15], v[14:15], v[42:43], v[138:139]
	v_fma_f32 v150, v145, v67, v130
	v_pk_fma_f32 v[16:17], v[16:17], v[40:41], v[140:141]
	v_pk_fma_f32 v[18:19], v[18:19], v[42:43], v[142:143]
	v_fmac_f32_e32 v150, v144, v66
	s_waitcnt lgkmcnt(0)
	ds_read_b128 v[52:55], v147 offset:22128
	ds_read_b128 v[56:59], v147 offset:22384
	ds_read_b128 v[44:47], v147 offset:21616
	ds_read_b64 v[62:63], v148 offset:22640
	ds_read_b128 v[48:51], v147 offset:21872
	ds_read_b128 v[40:43], v147 offset:21360
	ds_read_b64 v[66:67], v149 offset:22768
	v_mul_f32_e32 v120, v12, v32
	v_mul_f32_e32 v121, v16, v32
	v_mul_f32_e32 v122, v12, v36
	v_mul_f32_e32 v123, v16, v36
	v_fmac_f32_e32 v120, v13, v33
	v_fmac_f32_e32 v121, v17, v33
	v_fmac_f32_e32 v122, v13, v37
	v_fmac_f32_e32 v123, v17, v37
	v_fmac_f32_e32 v120, v14, v34
	v_fmac_f32_e32 v121, v18, v34
	v_fmac_f32_e32 v122, v14, v38
	v_fmac_f32_e32 v123, v18, v38
	v_fmac_f32_e32 v120, v15, v35
	v_fmac_f32_e32 v121, v19, v35
	v_fmac_f32_e32 v122, v15, v39
	v_fmac_f32_e32 v123, v19, v39
	v_cndmask_b32_e64 v124, v120, v121, s[42:43]
	v_cndmask_b32_e64 v126, v122, v123, s[42:43]
	v_cndmask_b32_e64 v125, v121, v120, s[42:43]
	v_cndmask_b32_e64 v127, v123, v122, s[42:43]
	v_add_f32_dpp v124, v124, v125 quad_perm:[1,0,3,2] row_mask:0xf bank_mask:0xf bound_ctrl:1
	v_add_f32_dpp v126, v126, v127 quad_perm:[1,0,3,2] row_mask:0xf bank_mask:0xf bound_ctrl:1
	v_cndmask_b32_e64 v128, v124, v126, s[44:45]
	v_cndmask_b32_e64 v129, v126, v124, s[44:45]
	v_pk_mul_f32 v[136:137], v[24:25], v[60:61] op_sel_hi:[1,0]
	v_add_f32_dpp v130, v128, v129 quad_perm:[2,3,0,1] row_mask:0xf bank_mask:0xf bound_ctrl:1
	v_pk_mul_f32 v[138:139], v[26:27], v[60:61] op_sel_hi:[1,0]
	v_pk_mul_f32 v[140:141], v[24:25], v[60:61] op_sel:[0,1]
	v_add_f32_dpp v130, v130, v130 row_ror:4 row_mask:0xf bank_mask:0xf bound_ctrl:1
	v_pk_mul_f32 v[142:143], v[26:27], v[60:61] op_sel:[0,1]
	v_cndmask_b32_e64 v145, v61, v60, s[42:43]
	v_add_f32_dpp v130, v130, v130 row_ror:8 row_mask:0xf bank_mask:0xf bound_ctrl:1
	v_cndmask_b32_e32 v1, v1, v150, vcc
	s_nop 0
	v_mov_b32_dpp v132, v130 quad_perm:[0,0,0,0] row_mask:0xf bank_mask:0xf bound_ctrl:1
	v_mov_b32_dpp v134, v130 quad_perm:[1,1,1,1] row_mask:0xf bank_mask:0xf bound_ctrl:1
	v_pk_fma_f32 v[136:137], v[28:29], v[132:133], v[136:137] op_sel_hi:[1,0,1]
	v_pk_fma_f32 v[138:139], v[30:31], v[132:133], v[138:139] op_sel_hi:[1,0,1]
	v_pk_fma_f32 v[140:141], v[28:29], v[134:135], v[140:141] op_sel_hi:[1,0,1]
	v_pk_fma_f32 v[142:143], v[30:31], v[134:135], v[142:143] op_sel_hi:[1,0,1]
	v_cndmask_b32_e64 v144, v134, v132, s[42:43]
	v_pk_fma_f32 v[12:13], v[12:13], v[20:21], v[136:137]
	v_pk_fma_f32 v[14:15], v[14:15], v[22:23], v[138:139]
	v_fma_f32 v146, v145, v65, v130
	v_pk_fma_f32 v[16:17], v[16:17], v[20:21], v[140:141]
	v_pk_fma_f32 v[18:19], v[18:19], v[22:23], v[142:143]
	v_fmac_f32_e32 v146, v144, v64
	s_waitcnt lgkmcnt(0)
	ds_read_b128 v[32:35], v147 offset:23552
	ds_read_b128 v[36:39], v147 offset:23808
	ds_read_b128 v[24:27], v147 offset:23040
	ds_read_b64 v[60:61], v148 offset:24064
	ds_read_b128 v[28:31], v147 offset:23296
	ds_read_b128 v[20:23], v147 offset:22784
	ds_read_b64 v[64:65], v149 offset:24192
	v_mul_f32_e32 v120, v12, v52
	v_mul_f32_e32 v121, v16, v52
	v_mul_f32_e32 v122, v12, v56
	v_mul_f32_e32 v123, v16, v56
	v_fmac_f32_e32 v120, v13, v53
	v_fmac_f32_e32 v121, v17, v53
	v_fmac_f32_e32 v122, v13, v57
	v_fmac_f32_e32 v123, v17, v57
	v_fmac_f32_e32 v120, v14, v54
	v_fmac_f32_e32 v121, v18, v54
	v_fmac_f32_e32 v122, v14, v58
	v_fmac_f32_e32 v123, v18, v58
	v_fmac_f32_e32 v120, v15, v55
	v_fmac_f32_e32 v121, v19, v55
	v_fmac_f32_e32 v122, v15, v59
	v_fmac_f32_e32 v123, v19, v59
	v_cndmask_b32_e64 v124, v120, v121, s[42:43]
	v_cndmask_b32_e64 v126, v122, v123, s[42:43]
	v_cndmask_b32_e64 v125, v121, v120, s[42:43]
	v_cndmask_b32_e64 v127, v123, v122, s[42:43]
	v_add_f32_dpp v124, v124, v125 quad_perm:[1,0,3,2] row_mask:0xf bank_mask:0xf bound_ctrl:1
	v_add_f32_dpp v126, v126, v127 quad_perm:[1,0,3,2] row_mask:0xf bank_mask:0xf bound_ctrl:1
	v_cndmask_b32_e64 v128, v124, v126, s[44:45]
	v_cndmask_b32_e64 v129, v126, v124, s[44:45]
	v_pk_mul_f32 v[136:137], v[44:45], v[62:63] op_sel_hi:[1,0]
	v_add_f32_dpp v130, v128, v129 quad_perm:[2,3,0,1] row_mask:0xf bank_mask:0xf bound_ctrl:1
	v_pk_mul_f32 v[138:139], v[46:47], v[62:63] op_sel_hi:[1,0]
	v_pk_mul_f32 v[140:141], v[44:45], v[62:63] op_sel:[0,1]
	v_add_f32_dpp v130, v130, v130 row_ror:4 row_mask:0xf bank_mask:0xf bound_ctrl:1
	v_pk_mul_f32 v[142:143], v[46:47], v[62:63] op_sel:[0,1]
	v_cndmask_b32_e64 v145, v63, v62, s[42:43]
	v_add_f32_dpp v130, v130, v130 row_ror:8 row_mask:0xf bank_mask:0xf bound_ctrl:1
	v_cndmask_b32_e32 v2, v2, v146, vcc
	s_nop 0
	v_mov_b32_dpp v132, v130 quad_perm:[0,0,0,0] row_mask:0xf bank_mask:0xf bound_ctrl:1
	v_mov_b32_dpp v134, v130 quad_perm:[1,1,1,1] row_mask:0xf bank_mask:0xf bound_ctrl:1
	v_pk_fma_f32 v[136:137], v[48:49], v[132:133], v[136:137] op_sel_hi:[1,0,1]
	v_pk_fma_f32 v[138:139], v[50:51], v[132:133], v[138:139] op_sel_hi:[1,0,1]
	v_pk_fma_f32 v[140:141], v[48:49], v[134:135], v[140:141] op_sel_hi:[1,0,1]
	v_pk_fma_f32 v[142:143], v[50:51], v[134:135], v[142:143] op_sel_hi:[1,0,1]
	v_cndmask_b32_e64 v144, v134, v132, s[42:43]
	v_pk_fma_f32 v[12:13], v[12:13], v[40:41], v[136:137]
	v_pk_fma_f32 v[14:15], v[14:15], v[42:43], v[138:139]
	v_fma_f32 v150, v145, v67, v130
	v_pk_fma_f32 v[16:17], v[16:17], v[40:41], v[140:141]
	v_pk_fma_f32 v[18:19], v[18:19], v[42:43], v[142:143]
	v_fmac_f32_e32 v150, v144, v66
	s_waitcnt lgkmcnt(0)
	ds_read_b128 v[52:55], v147 offset:24976
	ds_read_b128 v[56:59], v147 offset:25232
	ds_read_b128 v[44:47], v147 offset:24464
	ds_read_b64 v[62:63], v148 offset:25488
	ds_read_b128 v[48:51], v147 offset:24720
	ds_read_b128 v[40:43], v147 offset:24208
	ds_read_b64 v[66:67], v149 offset:25616
	v_mul_f32_e32 v120, v12, v32
	v_mul_f32_e32 v121, v16, v32
	v_mul_f32_e32 v122, v12, v36
	v_mul_f32_e32 v123, v16, v36
	v_fmac_f32_e32 v120, v13, v33
	v_fmac_f32_e32 v121, v17, v33
	v_fmac_f32_e32 v122, v13, v37
	v_fmac_f32_e32 v123, v17, v37
	v_fmac_f32_e32 v120, v14, v34
	v_fmac_f32_e32 v121, v18, v34
	v_fmac_f32_e32 v122, v14, v38
	v_fmac_f32_e32 v123, v18, v38
	v_fmac_f32_e32 v120, v15, v35
	v_fmac_f32_e32 v121, v19, v35
	v_fmac_f32_e32 v122, v15, v39
	v_fmac_f32_e32 v123, v19, v39
	v_cndmask_b32_e64 v124, v120, v121, s[42:43]
	v_cndmask_b32_e64 v126, v122, v123, s[42:43]
	v_cndmask_b32_e64 v125, v121, v120, s[42:43]
	v_cndmask_b32_e64 v127, v123, v122, s[42:43]
	v_add_f32_dpp v124, v124, v125 quad_perm:[1,0,3,2] row_mask:0xf bank_mask:0xf bound_ctrl:1
	v_add_f32_dpp v126, v126, v127 quad_perm:[1,0,3,2] row_mask:0xf bank_mask:0xf bound_ctrl:1
	v_cndmask_b32_e64 v128, v124, v126, s[44:45]
	v_cndmask_b32_e64 v129, v126, v124, s[44:45]
	v_pk_mul_f32 v[136:137], v[24:25], v[60:61] op_sel_hi:[1,0]
	v_add_f32_dpp v130, v128, v129 quad_perm:[2,3,0,1] row_mask:0xf bank_mask:0xf bound_ctrl:1
	v_pk_mul_f32 v[138:139], v[26:27], v[60:61] op_sel_hi:[1,0]
	v_pk_mul_f32 v[140:141], v[24:25], v[60:61] op_sel:[0,1]
	v_add_f32_dpp v130, v130, v130 row_ror:4 row_mask:0xf bank_mask:0xf bound_ctrl:1
	v_pk_mul_f32 v[142:143], v[26:27], v[60:61] op_sel:[0,1]
	v_cndmask_b32_e64 v145, v61, v60, s[42:43]
	v_add_f32_dpp v130, v130, v130 row_ror:8 row_mask:0xf bank_mask:0xf bound_ctrl:1
	v_cndmask_b32_e32 v3, v3, v150, vcc
	v_cmp_eq_u32_e32 vcc, 0, v119
	v_mov_b32_dpp v132, v130 quad_perm:[0,0,0,0] row_mask:0xf bank_mask:0xf bound_ctrl:1
	v_mov_b32_dpp v134, v130 quad_perm:[1,1,1,1] row_mask:0xf bank_mask:0xf bound_ctrl:1
	v_pk_fma_f32 v[136:137], v[28:29], v[132:133], v[136:137] op_sel_hi:[1,0,1]
	v_pk_fma_f32 v[138:139], v[30:31], v[132:133], v[138:139] op_sel_hi:[1,0,1]
	v_pk_fma_f32 v[140:141], v[28:29], v[134:135], v[140:141] op_sel_hi:[1,0,1]
	v_pk_fma_f32 v[142:143], v[30:31], v[134:135], v[142:143] op_sel_hi:[1,0,1]
	v_cndmask_b32_e64 v144, v134, v132, s[42:43]
	v_pk_fma_f32 v[12:13], v[12:13], v[20:21], v[136:137]
	v_pk_fma_f32 v[14:15], v[14:15], v[22:23], v[138:139]
	v_fma_f32 v146, v145, v65, v130
	v_pk_fma_f32 v[16:17], v[16:17], v[20:21], v[140:141]
	v_pk_fma_f32 v[18:19], v[18:19], v[22:23], v[142:143]
	v_fmac_f32_e32 v146, v144, v64
	s_waitcnt lgkmcnt(0)
	ds_read_b128 v[32:35], v147 offset:26400
	ds_read_b128 v[36:39], v147 offset:26656
	ds_read_b128 v[24:27], v147 offset:25888
	ds_read_b64 v[60:61], v148 offset:26912
	ds_read_b128 v[28:31], v147 offset:26144
	ds_read_b128 v[20:23], v147 offset:25632
	ds_read_b64 v[64:65], v149 offset:27040
	v_mul_f32_e32 v120, v12, v52
	v_mul_f32_e32 v121, v16, v52
	v_mul_f32_e32 v122, v12, v56
	v_mul_f32_e32 v123, v16, v56
	v_fmac_f32_e32 v120, v13, v53
	v_fmac_f32_e32 v121, v17, v53
	v_fmac_f32_e32 v122, v13, v57
	v_fmac_f32_e32 v123, v17, v57
	v_fmac_f32_e32 v120, v14, v54
	v_fmac_f32_e32 v121, v18, v54
	v_fmac_f32_e32 v122, v14, v58
	v_fmac_f32_e32 v123, v18, v58
	v_fmac_f32_e32 v120, v15, v55
	v_fmac_f32_e32 v121, v19, v55
	v_fmac_f32_e32 v122, v15, v59
	v_fmac_f32_e32 v123, v19, v59
	v_cndmask_b32_e64 v124, v120, v121, s[42:43]
	v_cndmask_b32_e64 v126, v122, v123, s[42:43]
	v_cndmask_b32_e64 v125, v121, v120, s[42:43]
	v_cndmask_b32_e64 v127, v123, v122, s[42:43]
	v_add_f32_dpp v124, v124, v125 quad_perm:[1,0,3,2] row_mask:0xf bank_mask:0xf bound_ctrl:1
	v_add_f32_dpp v126, v126, v127 quad_perm:[1,0,3,2] row_mask:0xf bank_mask:0xf bound_ctrl:1
	v_cndmask_b32_e64 v128, v124, v126, s[44:45]
	v_cndmask_b32_e64 v129, v126, v124, s[44:45]
	v_pk_mul_f32 v[136:137], v[44:45], v[62:63] op_sel_hi:[1,0]
	v_add_f32_dpp v130, v128, v129 quad_perm:[2,3,0,1] row_mask:0xf bank_mask:0xf bound_ctrl:1
	v_pk_mul_f32 v[138:139], v[46:47], v[62:63] op_sel_hi:[1,0]
	v_pk_mul_f32 v[140:141], v[44:45], v[62:63] op_sel:[0,1]
	v_add_f32_dpp v130, v130, v130 row_ror:4 row_mask:0xf bank_mask:0xf bound_ctrl:1
	v_pk_mul_f32 v[142:143], v[46:47], v[62:63] op_sel:[0,1]
	v_cndmask_b32_e64 v145, v63, v62, s[42:43]
	v_add_f32_dpp v130, v130, v130 row_ror:8 row_mask:0xf bank_mask:0xf bound_ctrl:1
	v_cndmask_b32_e32 v4, v4, v146, vcc
	s_nop 0
	v_mov_b32_dpp v132, v130 quad_perm:[0,0,0,0] row_mask:0xf bank_mask:0xf bound_ctrl:1
	v_mov_b32_dpp v134, v130 quad_perm:[1,1,1,1] row_mask:0xf bank_mask:0xf bound_ctrl:1
	v_pk_fma_f32 v[136:137], v[48:49], v[132:133], v[136:137] op_sel_hi:[1,0,1]
	v_pk_fma_f32 v[138:139], v[50:51], v[132:133], v[138:139] op_sel_hi:[1,0,1]
	v_pk_fma_f32 v[140:141], v[48:49], v[134:135], v[140:141] op_sel_hi:[1,0,1]
	v_pk_fma_f32 v[142:143], v[50:51], v[134:135], v[142:143] op_sel_hi:[1,0,1]
	v_cndmask_b32_e64 v144, v134, v132, s[42:43]
	v_pk_fma_f32 v[12:13], v[12:13], v[40:41], v[136:137]
	v_pk_fma_f32 v[14:15], v[14:15], v[42:43], v[138:139]
	v_fma_f32 v150, v145, v67, v130
	v_pk_fma_f32 v[16:17], v[16:17], v[40:41], v[140:141]
	v_pk_fma_f32 v[18:19], v[18:19], v[42:43], v[142:143]
	v_fmac_f32_e32 v150, v144, v66
	s_waitcnt lgkmcnt(0)
	ds_read_b128 v[52:55], v147 offset:27824
	ds_read_b128 v[56:59], v147 offset:28080
	ds_read_b128 v[44:47], v147 offset:27312
	ds_read_b64 v[62:63], v148 offset:28336
	ds_read_b128 v[48:51], v147 offset:27568
	ds_read_b128 v[40:43], v147 offset:27056
	ds_read_b64 v[66:67], v149 offset:28464
	v_mul_f32_e32 v120, v12, v32
	v_mul_f32_e32 v121, v16, v32
	v_mul_f32_e32 v122, v12, v36
	v_mul_f32_e32 v123, v16, v36
	v_fmac_f32_e32 v120, v13, v33
	v_fmac_f32_e32 v121, v17, v33
	v_fmac_f32_e32 v122, v13, v37
	v_fmac_f32_e32 v123, v17, v37
	v_fmac_f32_e32 v120, v14, v34
	v_fmac_f32_e32 v121, v18, v34
	v_fmac_f32_e32 v122, v14, v38
	v_fmac_f32_e32 v123, v18, v38
	v_fmac_f32_e32 v120, v15, v35
	v_fmac_f32_e32 v121, v19, v35
	v_fmac_f32_e32 v122, v15, v39
	v_fmac_f32_e32 v123, v19, v39
	v_cndmask_b32_e64 v124, v120, v121, s[42:43]
	v_cndmask_b32_e64 v126, v122, v123, s[42:43]
	v_cndmask_b32_e64 v125, v121, v120, s[42:43]
	v_cndmask_b32_e64 v127, v123, v122, s[42:43]
	v_add_f32_dpp v124, v124, v125 quad_perm:[1,0,3,2] row_mask:0xf bank_mask:0xf bound_ctrl:1
	v_add_f32_dpp v126, v126, v127 quad_perm:[1,0,3,2] row_mask:0xf bank_mask:0xf bound_ctrl:1
	v_cndmask_b32_e64 v128, v124, v126, s[44:45]
	v_cndmask_b32_e64 v129, v126, v124, s[44:45]
	v_pk_mul_f32 v[136:137], v[24:25], v[60:61] op_sel_hi:[1,0]
	v_add_f32_dpp v130, v128, v129 quad_perm:[2,3,0,1] row_mask:0xf bank_mask:0xf bound_ctrl:1
	v_pk_mul_f32 v[138:139], v[26:27], v[60:61] op_sel_hi:[1,0]
	v_pk_mul_f32 v[140:141], v[24:25], v[60:61] op_sel:[0,1]
	v_add_f32_dpp v130, v130, v130 row_ror:4 row_mask:0xf bank_mask:0xf bound_ctrl:1
	v_pk_mul_f32 v[142:143], v[26:27], v[60:61] op_sel:[0,1]
	v_cndmask_b32_e64 v145, v61, v60, s[42:43]
	v_add_f32_dpp v130, v130, v130 row_ror:8 row_mask:0xf bank_mask:0xf bound_ctrl:1
	v_cndmask_b32_e32 v5, v5, v150, vcc
	s_nop 0
	v_mov_b32_dpp v132, v130 quad_perm:[0,0,0,0] row_mask:0xf bank_mask:0xf bound_ctrl:1
	v_mov_b32_dpp v134, v130 quad_perm:[1,1,1,1] row_mask:0xf bank_mask:0xf bound_ctrl:1
	v_pk_fma_f32 v[136:137], v[28:29], v[132:133], v[136:137] op_sel_hi:[1,0,1]
	v_pk_fma_f32 v[138:139], v[30:31], v[132:133], v[138:139] op_sel_hi:[1,0,1]
	v_pk_fma_f32 v[140:141], v[28:29], v[134:135], v[140:141] op_sel_hi:[1,0,1]
	v_pk_fma_f32 v[142:143], v[30:31], v[134:135], v[142:143] op_sel_hi:[1,0,1]
	v_cndmask_b32_e64 v144, v134, v132, s[42:43]
	v_pk_fma_f32 v[12:13], v[12:13], v[20:21], v[136:137]
	v_pk_fma_f32 v[14:15], v[14:15], v[22:23], v[138:139]
	v_fma_f32 v146, v145, v65, v130
	v_pk_fma_f32 v[16:17], v[16:17], v[20:21], v[140:141]
	v_pk_fma_f32 v[18:19], v[18:19], v[22:23], v[142:143]
	v_fmac_f32_e32 v146, v144, v64
	s_waitcnt lgkmcnt(0)
	ds_read_b128 v[32:35], v147 offset:29248
	ds_read_b128 v[36:39], v147 offset:29504
	ds_read_b128 v[24:27], v147 offset:28736
	ds_read_b64 v[60:61], v148 offset:29760
	ds_read_b128 v[28:31], v147 offset:28992
	ds_read_b128 v[20:23], v147 offset:28480
	ds_read_b64 v[64:65], v149 offset:29888
	v_mul_f32_e32 v120, v12, v52
	v_mul_f32_e32 v121, v16, v52
	v_mul_f32_e32 v122, v12, v56
	v_mul_f32_e32 v123, v16, v56
	v_fmac_f32_e32 v120, v13, v53
	v_fmac_f32_e32 v121, v17, v53
	v_fmac_f32_e32 v122, v13, v57
	v_fmac_f32_e32 v123, v17, v57
	v_fmac_f32_e32 v120, v14, v54
	v_fmac_f32_e32 v121, v18, v54
	v_fmac_f32_e32 v122, v14, v58
	v_fmac_f32_e32 v123, v18, v58
	v_fmac_f32_e32 v120, v15, v55
	v_fmac_f32_e32 v121, v19, v55
	v_fmac_f32_e32 v122, v15, v59
	v_fmac_f32_e32 v123, v19, v59
	v_cndmask_b32_e64 v124, v120, v121, s[42:43]
	v_cndmask_b32_e64 v126, v122, v123, s[42:43]
	v_cndmask_b32_e64 v125, v121, v120, s[42:43]
	v_cndmask_b32_e64 v127, v123, v122, s[42:43]
	v_add_f32_dpp v124, v124, v125 quad_perm:[1,0,3,2] row_mask:0xf bank_mask:0xf bound_ctrl:1
	v_add_f32_dpp v126, v126, v127 quad_perm:[1,0,3,2] row_mask:0xf bank_mask:0xf bound_ctrl:1
	v_cndmask_b32_e64 v128, v124, v126, s[44:45]
	v_cndmask_b32_e64 v129, v126, v124, s[44:45]
	v_pk_mul_f32 v[136:137], v[44:45], v[62:63] op_sel_hi:[1,0]
	v_add_f32_dpp v130, v128, v129 quad_perm:[2,3,0,1] row_mask:0xf bank_mask:0xf bound_ctrl:1
	v_pk_mul_f32 v[138:139], v[46:47], v[62:63] op_sel_hi:[1,0]
	v_pk_mul_f32 v[140:141], v[44:45], v[62:63] op_sel:[0,1]
	v_add_f32_dpp v130, v130, v130 row_ror:4 row_mask:0xf bank_mask:0xf bound_ctrl:1
	v_pk_mul_f32 v[142:143], v[46:47], v[62:63] op_sel:[0,1]
	v_cndmask_b32_e64 v145, v63, v62, s[42:43]
	v_add_f32_dpp v130, v130, v130 row_ror:8 row_mask:0xf bank_mask:0xf bound_ctrl:1
	v_cndmask_b32_e32 v6, v6, v146, vcc
	s_nop 0
	v_mov_b32_dpp v132, v130 quad_perm:[0,0,0,0] row_mask:0xf bank_mask:0xf bound_ctrl:1
	v_mov_b32_dpp v134, v130 quad_perm:[1,1,1,1] row_mask:0xf bank_mask:0xf bound_ctrl:1
	v_pk_fma_f32 v[136:137], v[48:49], v[132:133], v[136:137] op_sel_hi:[1,0,1]
	v_pk_fma_f32 v[138:139], v[50:51], v[132:133], v[138:139] op_sel_hi:[1,0,1]
	v_pk_fma_f32 v[140:141], v[48:49], v[134:135], v[140:141] op_sel_hi:[1,0,1]
	v_pk_fma_f32 v[142:143], v[50:51], v[134:135], v[142:143] op_sel_hi:[1,0,1]
	v_cndmask_b32_e64 v144, v134, v132, s[42:43]
	v_pk_fma_f32 v[12:13], v[12:13], v[40:41], v[136:137]
	v_pk_fma_f32 v[14:15], v[14:15], v[42:43], v[138:139]
	v_fma_f32 v150, v145, v67, v130
	v_pk_fma_f32 v[16:17], v[16:17], v[40:41], v[140:141]
	v_pk_fma_f32 v[18:19], v[18:19], v[42:43], v[142:143]
	v_fmac_f32_e32 v150, v144, v66
	s_waitcnt lgkmcnt(0)
	ds_read_b128 v[52:55], v147 offset:30672
	ds_read_b128 v[56:59], v147 offset:30928
	ds_read_b128 v[44:47], v147 offset:30160
	ds_read_b64 v[62:63], v148 offset:31184
	ds_read_b128 v[48:51], v147 offset:30416
	ds_read_b128 v[40:43], v147 offset:29904
	ds_read_b64 v[66:67], v149 offset:31312
	v_mul_f32_e32 v120, v12, v32
	v_mul_f32_e32 v121, v16, v32
	v_mul_f32_e32 v122, v12, v36
	v_mul_f32_e32 v123, v16, v36
	v_fmac_f32_e32 v120, v13, v33
	v_fmac_f32_e32 v121, v17, v33
	v_fmac_f32_e32 v122, v13, v37
	v_fmac_f32_e32 v123, v17, v37
	v_fmac_f32_e32 v120, v14, v34
	v_fmac_f32_e32 v121, v18, v34
	v_fmac_f32_e32 v122, v14, v38
	v_fmac_f32_e32 v123, v18, v38
	v_fmac_f32_e32 v120, v15, v35
	v_fmac_f32_e32 v121, v19, v35
	v_fmac_f32_e32 v122, v15, v39
	v_fmac_f32_e32 v123, v19, v39
	v_cndmask_b32_e64 v124, v120, v121, s[42:43]
	v_cndmask_b32_e64 v126, v122, v123, s[42:43]
	v_cndmask_b32_e64 v125, v121, v120, s[42:43]
	v_cndmask_b32_e64 v127, v123, v122, s[42:43]
	v_add_f32_dpp v124, v124, v125 quad_perm:[1,0,3,2] row_mask:0xf bank_mask:0xf bound_ctrl:1
	v_add_f32_dpp v126, v126, v127 quad_perm:[1,0,3,2] row_mask:0xf bank_mask:0xf bound_ctrl:1
	v_cndmask_b32_e64 v128, v124, v126, s[44:45]
	v_cndmask_b32_e64 v129, v126, v124, s[44:45]
	v_pk_mul_f32 v[136:137], v[24:25], v[60:61] op_sel_hi:[1,0]
	v_add_f32_dpp v130, v128, v129 quad_perm:[2,3,0,1] row_mask:0xf bank_mask:0xf bound_ctrl:1
	v_pk_mul_f32 v[138:139], v[26:27], v[60:61] op_sel_hi:[1,0]
	v_pk_mul_f32 v[140:141], v[24:25], v[60:61] op_sel:[0,1]
	v_add_f32_dpp v130, v130, v130 row_ror:4 row_mask:0xf bank_mask:0xf bound_ctrl:1
	v_pk_mul_f32 v[142:143], v[26:27], v[60:61] op_sel:[0,1]
	v_cndmask_b32_e64 v145, v61, v60, s[42:43]
	v_add_f32_dpp v130, v130, v130 row_ror:8 row_mask:0xf bank_mask:0xf bound_ctrl:1
	v_cndmask_b32_e32 v7, v7, v150, vcc
	v_cmp_eq_u32_e32 vcc, 1, v119
	v_mov_b32_dpp v132, v130 quad_perm:[0,0,0,0] row_mask:0xf bank_mask:0xf bound_ctrl:1
	v_mov_b32_dpp v134, v130 quad_perm:[1,1,1,1] row_mask:0xf bank_mask:0xf bound_ctrl:1
	v_pk_fma_f32 v[136:137], v[28:29], v[132:133], v[136:137] op_sel_hi:[1,0,1]
	v_pk_fma_f32 v[138:139], v[30:31], v[132:133], v[138:139] op_sel_hi:[1,0,1]
	v_pk_fma_f32 v[140:141], v[28:29], v[134:135], v[140:141] op_sel_hi:[1,0,1]
	v_pk_fma_f32 v[142:143], v[30:31], v[134:135], v[142:143] op_sel_hi:[1,0,1]
	v_cndmask_b32_e64 v144, v134, v132, s[42:43]
	v_pk_fma_f32 v[12:13], v[12:13], v[20:21], v[136:137]
	v_pk_fma_f32 v[14:15], v[14:15], v[22:23], v[138:139]
	v_fma_f32 v146, v145, v65, v130
	v_pk_fma_f32 v[16:17], v[16:17], v[20:21], v[140:141]
	v_pk_fma_f32 v[18:19], v[18:19], v[22:23], v[142:143]
	v_fmac_f32_e32 v146, v144, v64
	s_waitcnt lgkmcnt(0)
	ds_read_b128 v[32:35], v147 offset:32096
	ds_read_b128 v[36:39], v147 offset:32352
	ds_read_b128 v[24:27], v147 offset:31584
	ds_read_b64 v[60:61], v148 offset:32608
	ds_read_b128 v[28:31], v147 offset:31840
	ds_read_b128 v[20:23], v147 offset:31328
	ds_read_b64 v[64:65], v149 offset:32736
	v_mul_f32_e32 v120, v12, v52
	v_mul_f32_e32 v121, v16, v52
	v_mul_f32_e32 v122, v12, v56
	v_mul_f32_e32 v123, v16, v56
	v_fmac_f32_e32 v120, v13, v53
	v_fmac_f32_e32 v121, v17, v53
	v_fmac_f32_e32 v122, v13, v57
	v_fmac_f32_e32 v123, v17, v57
	v_fmac_f32_e32 v120, v14, v54
	v_fmac_f32_e32 v121, v18, v54
	v_fmac_f32_e32 v122, v14, v58
	v_fmac_f32_e32 v123, v18, v58
	v_fmac_f32_e32 v120, v15, v55
	v_fmac_f32_e32 v121, v19, v55
	v_fmac_f32_e32 v122, v15, v59
	v_fmac_f32_e32 v123, v19, v59
	v_cndmask_b32_e64 v124, v120, v121, s[42:43]
	v_cndmask_b32_e64 v126, v122, v123, s[42:43]
	v_cndmask_b32_e64 v125, v121, v120, s[42:43]
	v_cndmask_b32_e64 v127, v123, v122, s[42:43]
	v_add_f32_dpp v124, v124, v125 quad_perm:[1,0,3,2] row_mask:0xf bank_mask:0xf bound_ctrl:1
	v_add_f32_dpp v126, v126, v127 quad_perm:[1,0,3,2] row_mask:0xf bank_mask:0xf bound_ctrl:1
	v_cndmask_b32_e64 v128, v124, v126, s[44:45]
	v_cndmask_b32_e64 v129, v126, v124, s[44:45]
	v_pk_mul_f32 v[136:137], v[44:45], v[62:63] op_sel_hi:[1,0]
	v_add_f32_dpp v130, v128, v129 quad_perm:[2,3,0,1] row_mask:0xf bank_mask:0xf bound_ctrl:1
	v_pk_mul_f32 v[138:139], v[46:47], v[62:63] op_sel_hi:[1,0]
	v_pk_mul_f32 v[140:141], v[44:45], v[62:63] op_sel:[0,1]
	v_add_f32_dpp v130, v130, v130 row_ror:4 row_mask:0xf bank_mask:0xf bound_ctrl:1
	v_pk_mul_f32 v[142:143], v[46:47], v[62:63] op_sel:[0,1]
	v_cndmask_b32_e64 v145, v63, v62, s[42:43]
	v_add_f32_dpp v130, v130, v130 row_ror:8 row_mask:0xf bank_mask:0xf bound_ctrl:1
	v_cndmask_b32_e32 v4, v4, v146, vcc
	s_nop 0
	v_mov_b32_dpp v132, v130 quad_perm:[0,0,0,0] row_mask:0xf bank_mask:0xf bound_ctrl:1
	v_mov_b32_dpp v134, v130 quad_perm:[1,1,1,1] row_mask:0xf bank_mask:0xf bound_ctrl:1
	v_pk_fma_f32 v[136:137], v[48:49], v[132:133], v[136:137] op_sel_hi:[1,0,1]
	v_pk_fma_f32 v[138:139], v[50:51], v[132:133], v[138:139] op_sel_hi:[1,0,1]
	v_pk_fma_f32 v[140:141], v[48:49], v[134:135], v[140:141] op_sel_hi:[1,0,1]
	v_pk_fma_f32 v[142:143], v[50:51], v[134:135], v[142:143] op_sel_hi:[1,0,1]
	v_cndmask_b32_e64 v144, v134, v132, s[42:43]
	v_pk_fma_f32 v[12:13], v[12:13], v[40:41], v[136:137]
	v_pk_fma_f32 v[14:15], v[14:15], v[42:43], v[138:139]
	v_fma_f32 v150, v145, v67, v130
	v_pk_fma_f32 v[16:17], v[16:17], v[40:41], v[140:141]
	v_pk_fma_f32 v[18:19], v[18:19], v[42:43], v[142:143]
	v_fmac_f32_e32 v150, v144, v66
	s_waitcnt lgkmcnt(0)
	ds_read_b128 v[52:55], v147 offset:33520
	ds_read_b128 v[56:59], v147 offset:33776
	ds_read_b128 v[44:47], v147 offset:33008
	ds_read_b64 v[62:63], v148 offset:34032
	ds_read_b128 v[48:51], v147 offset:33264
	ds_read_b128 v[40:43], v147 offset:32752
	ds_read_b64 v[66:67], v149 offset:34160
	v_mul_f32_e32 v120, v12, v32
	v_mul_f32_e32 v121, v16, v32
	v_mul_f32_e32 v122, v12, v36
	v_mul_f32_e32 v123, v16, v36
	v_fmac_f32_e32 v120, v13, v33
	v_fmac_f32_e32 v121, v17, v33
	v_fmac_f32_e32 v122, v13, v37
	v_fmac_f32_e32 v123, v17, v37
	v_fmac_f32_e32 v120, v14, v34
	v_fmac_f32_e32 v121, v18, v34
	v_fmac_f32_e32 v122, v14, v38
	v_fmac_f32_e32 v123, v18, v38
	v_fmac_f32_e32 v120, v15, v35
	v_fmac_f32_e32 v121, v19, v35
	v_fmac_f32_e32 v122, v15, v39
	v_fmac_f32_e32 v123, v19, v39
	v_cndmask_b32_e64 v124, v120, v121, s[42:43]
	v_cndmask_b32_e64 v126, v122, v123, s[42:43]
	v_cndmask_b32_e64 v125, v121, v120, s[42:43]
	v_cndmask_b32_e64 v127, v123, v122, s[42:43]
	v_add_f32_dpp v124, v124, v125 quad_perm:[1,0,3,2] row_mask:0xf bank_mask:0xf bound_ctrl:1
	v_add_f32_dpp v126, v126, v127 quad_perm:[1,0,3,2] row_mask:0xf bank_mask:0xf bound_ctrl:1
	v_cndmask_b32_e64 v128, v124, v126, s[44:45]
	v_cndmask_b32_e64 v129, v126, v124, s[44:45]
	v_pk_mul_f32 v[136:137], v[24:25], v[60:61] op_sel_hi:[1,0]
	v_add_f32_dpp v130, v128, v129 quad_perm:[2,3,0,1] row_mask:0xf bank_mask:0xf bound_ctrl:1
	v_pk_mul_f32 v[138:139], v[26:27], v[60:61] op_sel_hi:[1,0]
	v_pk_mul_f32 v[140:141], v[24:25], v[60:61] op_sel:[0,1]
	v_add_f32_dpp v130, v130, v130 row_ror:4 row_mask:0xf bank_mask:0xf bound_ctrl:1
	v_pk_mul_f32 v[142:143], v[26:27], v[60:61] op_sel:[0,1]
	v_cndmask_b32_e64 v145, v61, v60, s[42:43]
	v_add_f32_dpp v130, v130, v130 row_ror:8 row_mask:0xf bank_mask:0xf bound_ctrl:1
	v_cndmask_b32_e32 v5, v5, v150, vcc
	s_nop 0
	v_mov_b32_dpp v132, v130 quad_perm:[0,0,0,0] row_mask:0xf bank_mask:0xf bound_ctrl:1
	v_mov_b32_dpp v134, v130 quad_perm:[1,1,1,1] row_mask:0xf bank_mask:0xf bound_ctrl:1
	v_pk_fma_f32 v[136:137], v[28:29], v[132:133], v[136:137] op_sel_hi:[1,0,1]
	v_pk_fma_f32 v[138:139], v[30:31], v[132:133], v[138:139] op_sel_hi:[1,0,1]
	v_pk_fma_f32 v[140:141], v[28:29], v[134:135], v[140:141] op_sel_hi:[1,0,1]
	v_pk_fma_f32 v[142:143], v[30:31], v[134:135], v[142:143] op_sel_hi:[1,0,1]
	v_cndmask_b32_e64 v144, v134, v132, s[42:43]
	v_pk_fma_f32 v[12:13], v[12:13], v[20:21], v[136:137]
	v_pk_fma_f32 v[14:15], v[14:15], v[22:23], v[138:139]
	v_fma_f32 v146, v145, v65, v130
	v_pk_fma_f32 v[16:17], v[16:17], v[20:21], v[140:141]
	v_pk_fma_f32 v[18:19], v[18:19], v[22:23], v[142:143]
	v_fmac_f32_e32 v146, v144, v64
	s_waitcnt lgkmcnt(0)
	ds_read_b128 v[32:35], v147 offset:34944
	ds_read_b128 v[36:39], v147 offset:35200
	ds_read_b128 v[24:27], v147 offset:34432
	ds_read_b64 v[60:61], v148 offset:35456
	ds_read_b128 v[28:31], v147 offset:34688
	ds_read_b128 v[20:23], v147 offset:34176
	ds_read_b64 v[64:65], v149 offset:35584
	v_mul_f32_e32 v120, v12, v52
	v_mul_f32_e32 v121, v16, v52
	v_mul_f32_e32 v122, v12, v56
	v_mul_f32_e32 v123, v16, v56
	v_fmac_f32_e32 v120, v13, v53
	v_fmac_f32_e32 v121, v17, v53
	v_fmac_f32_e32 v122, v13, v57
	v_fmac_f32_e32 v123, v17, v57
	v_fmac_f32_e32 v120, v14, v54
	v_fmac_f32_e32 v121, v18, v54
	v_fmac_f32_e32 v122, v14, v58
	v_fmac_f32_e32 v123, v18, v58
	v_fmac_f32_e32 v120, v15, v55
	v_fmac_f32_e32 v121, v19, v55
	v_fmac_f32_e32 v122, v15, v59
	v_fmac_f32_e32 v123, v19, v59
	v_cndmask_b32_e64 v124, v120, v121, s[42:43]
	v_cndmask_b32_e64 v126, v122, v123, s[42:43]
	v_cndmask_b32_e64 v125, v121, v120, s[42:43]
	v_cndmask_b32_e64 v127, v123, v122, s[42:43]
	v_add_f32_dpp v124, v124, v125 quad_perm:[1,0,3,2] row_mask:0xf bank_mask:0xf bound_ctrl:1
	v_add_f32_dpp v126, v126, v127 quad_perm:[1,0,3,2] row_mask:0xf bank_mask:0xf bound_ctrl:1
	v_cndmask_b32_e64 v128, v124, v126, s[44:45]
	v_cndmask_b32_e64 v129, v126, v124, s[44:45]
	v_pk_mul_f32 v[136:137], v[44:45], v[62:63] op_sel_hi:[1,0]
	v_add_f32_dpp v130, v128, v129 quad_perm:[2,3,0,1] row_mask:0xf bank_mask:0xf bound_ctrl:1
	v_pk_mul_f32 v[138:139], v[46:47], v[62:63] op_sel_hi:[1,0]
	v_pk_mul_f32 v[140:141], v[44:45], v[62:63] op_sel:[0,1]
	v_add_f32_dpp v130, v130, v130 row_ror:4 row_mask:0xf bank_mask:0xf bound_ctrl:1
	v_pk_mul_f32 v[142:143], v[46:47], v[62:63] op_sel:[0,1]
	v_cndmask_b32_e64 v145, v63, v62, s[42:43]
	v_add_f32_dpp v130, v130, v130 row_ror:8 row_mask:0xf bank_mask:0xf bound_ctrl:1
	v_cndmask_b32_e32 v6, v6, v146, vcc
	s_nop 0
	v_mov_b32_dpp v132, v130 quad_perm:[0,0,0,0] row_mask:0xf bank_mask:0xf bound_ctrl:1
	v_mov_b32_dpp v134, v130 quad_perm:[1,1,1,1] row_mask:0xf bank_mask:0xf bound_ctrl:1
	v_pk_fma_f32 v[136:137], v[48:49], v[132:133], v[136:137] op_sel_hi:[1,0,1]
	v_pk_fma_f32 v[138:139], v[50:51], v[132:133], v[138:139] op_sel_hi:[1,0,1]
	v_pk_fma_f32 v[140:141], v[48:49], v[134:135], v[140:141] op_sel_hi:[1,0,1]
	v_pk_fma_f32 v[142:143], v[50:51], v[134:135], v[142:143] op_sel_hi:[1,0,1]
	v_cndmask_b32_e64 v144, v134, v132, s[42:43]
	v_pk_fma_f32 v[12:13], v[12:13], v[40:41], v[136:137]
	v_pk_fma_f32 v[14:15], v[14:15], v[42:43], v[138:139]
	v_fma_f32 v150, v145, v67, v130
	v_pk_fma_f32 v[16:17], v[16:17], v[40:41], v[140:141]
	v_pk_fma_f32 v[18:19], v[18:19], v[42:43], v[142:143]
	v_fmac_f32_e32 v150, v144, v66
	s_waitcnt lgkmcnt(0)
	ds_read_b128 v[52:55], v147 offset:36368
	ds_read_b128 v[56:59], v147 offset:36624
	ds_read_b128 v[44:47], v147 offset:35856
	ds_read_b64 v[62:63], v148 offset:36880
	ds_read_b128 v[48:51], v147 offset:36112
	ds_read_b128 v[40:43], v147 offset:35600
	ds_read_b64 v[66:67], v149 offset:37008
	v_mul_f32_e32 v120, v12, v32
	v_mul_f32_e32 v121, v16, v32
	v_mul_f32_e32 v122, v12, v36
	v_mul_f32_e32 v123, v16, v36
	v_fmac_f32_e32 v120, v13, v33
	v_fmac_f32_e32 v121, v17, v33
	v_fmac_f32_e32 v122, v13, v37
	v_fmac_f32_e32 v123, v17, v37
	v_fmac_f32_e32 v120, v14, v34
	v_fmac_f32_e32 v121, v18, v34
	v_fmac_f32_e32 v122, v14, v38
	v_fmac_f32_e32 v123, v18, v38
	v_fmac_f32_e32 v120, v15, v35
	v_fmac_f32_e32 v121, v19, v35
	v_fmac_f32_e32 v122, v15, v39
	v_fmac_f32_e32 v123, v19, v39
	v_cndmask_b32_e64 v124, v120, v121, s[42:43]
	v_cndmask_b32_e64 v126, v122, v123, s[42:43]
	v_cndmask_b32_e64 v125, v121, v120, s[42:43]
	v_cndmask_b32_e64 v127, v123, v122, s[42:43]
	v_add_f32_dpp v124, v124, v125 quad_perm:[1,0,3,2] row_mask:0xf bank_mask:0xf bound_ctrl:1
	v_add_f32_dpp v126, v126, v127 quad_perm:[1,0,3,2] row_mask:0xf bank_mask:0xf bound_ctrl:1
	v_cndmask_b32_e64 v128, v124, v126, s[44:45]
	v_cndmask_b32_e64 v129, v126, v124, s[44:45]
	v_pk_mul_f32 v[136:137], v[24:25], v[60:61] op_sel_hi:[1,0]
	v_add_f32_dpp v130, v128, v129 quad_perm:[2,3,0,1] row_mask:0xf bank_mask:0xf bound_ctrl:1
	v_pk_mul_f32 v[138:139], v[26:27], v[60:61] op_sel_hi:[1,0]
	v_pk_mul_f32 v[140:141], v[24:25], v[60:61] op_sel:[0,1]
	v_add_f32_dpp v130, v130, v130 row_ror:4 row_mask:0xf bank_mask:0xf bound_ctrl:1
	v_pk_mul_f32 v[142:143], v[26:27], v[60:61] op_sel:[0,1]
	v_cndmask_b32_e64 v145, v61, v60, s[42:43]
	v_add_f32_dpp v130, v130, v130 row_ror:8 row_mask:0xf bank_mask:0xf bound_ctrl:1
	v_cndmask_b32_e32 v7, v7, v150, vcc
	v_cmp_eq_u32_e32 vcc, 2, v119
	v_mov_b32_dpp v132, v130 quad_perm:[0,0,0,0] row_mask:0xf bank_mask:0xf bound_ctrl:1
	v_mov_b32_dpp v134, v130 quad_perm:[1,1,1,1] row_mask:0xf bank_mask:0xf bound_ctrl:1
	v_pk_fma_f32 v[136:137], v[28:29], v[132:133], v[136:137] op_sel_hi:[1,0,1]
	v_pk_fma_f32 v[138:139], v[30:31], v[132:133], v[138:139] op_sel_hi:[1,0,1]
	v_pk_fma_f32 v[140:141], v[28:29], v[134:135], v[140:141] op_sel_hi:[1,0,1]
	v_pk_fma_f32 v[142:143], v[30:31], v[134:135], v[142:143] op_sel_hi:[1,0,1]
	v_cndmask_b32_e64 v144, v134, v132, s[42:43]
	v_pk_fma_f32 v[12:13], v[12:13], v[20:21], v[136:137]
	v_pk_fma_f32 v[14:15], v[14:15], v[22:23], v[138:139]
	v_fma_f32 v146, v145, v65, v130
	v_pk_fma_f32 v[16:17], v[16:17], v[20:21], v[140:141]
	v_pk_fma_f32 v[18:19], v[18:19], v[22:23], v[142:143]
	v_fmac_f32_e32 v146, v144, v64
	s_waitcnt lgkmcnt(0)
	ds_read_b128 v[32:35], v147 offset:37792
	ds_read_b128 v[36:39], v147 offset:38048
	ds_read_b128 v[24:27], v147 offset:37280
	ds_read_b64 v[60:61], v148 offset:38304
	ds_read_b128 v[28:31], v147 offset:37536
	ds_read_b128 v[20:23], v147 offset:37024
	ds_read_b64 v[64:65], v149 offset:38432
	v_mul_f32_e32 v120, v12, v52
	v_mul_f32_e32 v121, v16, v52
	v_mul_f32_e32 v122, v12, v56
	v_mul_f32_e32 v123, v16, v56
	v_fmac_f32_e32 v120, v13, v53
	v_fmac_f32_e32 v121, v17, v53
	v_fmac_f32_e32 v122, v13, v57
	v_fmac_f32_e32 v123, v17, v57
	v_fmac_f32_e32 v120, v14, v54
	v_fmac_f32_e32 v121, v18, v54
	v_fmac_f32_e32 v122, v14, v58
	v_fmac_f32_e32 v123, v18, v58
	v_fmac_f32_e32 v120, v15, v55
	v_fmac_f32_e32 v121, v19, v55
	v_fmac_f32_e32 v122, v15, v59
	v_fmac_f32_e32 v123, v19, v59
	v_cndmask_b32_e64 v124, v120, v121, s[42:43]
	v_cndmask_b32_e64 v126, v122, v123, s[42:43]
	v_cndmask_b32_e64 v125, v121, v120, s[42:43]
	v_cndmask_b32_e64 v127, v123, v122, s[42:43]
	v_add_f32_dpp v124, v124, v125 quad_perm:[1,0,3,2] row_mask:0xf bank_mask:0xf bound_ctrl:1
	v_add_f32_dpp v126, v126, v127 quad_perm:[1,0,3,2] row_mask:0xf bank_mask:0xf bound_ctrl:1
	v_cndmask_b32_e64 v128, v124, v126, s[44:45]
	v_cndmask_b32_e64 v129, v126, v124, s[44:45]
	v_pk_mul_f32 v[136:137], v[44:45], v[62:63] op_sel_hi:[1,0]
	v_add_f32_dpp v130, v128, v129 quad_perm:[2,3,0,1] row_mask:0xf bank_mask:0xf bound_ctrl:1
	v_pk_mul_f32 v[138:139], v[46:47], v[62:63] op_sel_hi:[1,0]
	v_pk_mul_f32 v[140:141], v[44:45], v[62:63] op_sel:[0,1]
	v_add_f32_dpp v130, v130, v130 row_ror:4 row_mask:0xf bank_mask:0xf bound_ctrl:1
	v_pk_mul_f32 v[142:143], v[46:47], v[62:63] op_sel:[0,1]
	v_cndmask_b32_e64 v145, v63, v62, s[42:43]
	v_add_f32_dpp v130, v130, v130 row_ror:8 row_mask:0xf bank_mask:0xf bound_ctrl:1
	v_cndmask_b32_e32 v4, v4, v146, vcc
	s_nop 0
	v_mov_b32_dpp v132, v130 quad_perm:[0,0,0,0] row_mask:0xf bank_mask:0xf bound_ctrl:1
	v_mov_b32_dpp v134, v130 quad_perm:[1,1,1,1] row_mask:0xf bank_mask:0xf bound_ctrl:1
	v_pk_fma_f32 v[136:137], v[48:49], v[132:133], v[136:137] op_sel_hi:[1,0,1]
	v_pk_fma_f32 v[138:139], v[50:51], v[132:133], v[138:139] op_sel_hi:[1,0,1]
	v_pk_fma_f32 v[140:141], v[48:49], v[134:135], v[140:141] op_sel_hi:[1,0,1]
	v_pk_fma_f32 v[142:143], v[50:51], v[134:135], v[142:143] op_sel_hi:[1,0,1]
	v_cndmask_b32_e64 v144, v134, v132, s[42:43]
	v_pk_fma_f32 v[12:13], v[12:13], v[40:41], v[136:137]
	v_pk_fma_f32 v[14:15], v[14:15], v[42:43], v[138:139]
	v_fma_f32 v150, v145, v67, v130
	v_pk_fma_f32 v[16:17], v[16:17], v[40:41], v[140:141]
	v_pk_fma_f32 v[18:19], v[18:19], v[42:43], v[142:143]
	v_fmac_f32_e32 v150, v144, v66
	s_waitcnt lgkmcnt(0)
	ds_read_b128 v[52:55], v147 offset:39216
	ds_read_b128 v[56:59], v147 offset:39472
	ds_read_b128 v[44:47], v147 offset:38704
	ds_read_b64 v[62:63], v148 offset:39728
	ds_read_b128 v[48:51], v147 offset:38960
	ds_read_b128 v[40:43], v147 offset:38448
	ds_read_b64 v[66:67], v149 offset:39856
	v_mul_f32_e32 v120, v12, v32
	v_mul_f32_e32 v121, v16, v32
	v_mul_f32_e32 v122, v12, v36
	v_mul_f32_e32 v123, v16, v36
	v_fmac_f32_e32 v120, v13, v33
	v_fmac_f32_e32 v121, v17, v33
	v_fmac_f32_e32 v122, v13, v37
	v_fmac_f32_e32 v123, v17, v37
	v_fmac_f32_e32 v120, v14, v34
	v_fmac_f32_e32 v121, v18, v34
	v_fmac_f32_e32 v122, v14, v38
	v_fmac_f32_e32 v123, v18, v38
	v_fmac_f32_e32 v120, v15, v35
	v_fmac_f32_e32 v121, v19, v35
	v_fmac_f32_e32 v122, v15, v39
	v_fmac_f32_e32 v123, v19, v39
	v_cndmask_b32_e64 v124, v120, v121, s[42:43]
	v_cndmask_b32_e64 v126, v122, v123, s[42:43]
	v_cndmask_b32_e64 v125, v121, v120, s[42:43]
	v_cndmask_b32_e64 v127, v123, v122, s[42:43]
	v_add_f32_dpp v124, v124, v125 quad_perm:[1,0,3,2] row_mask:0xf bank_mask:0xf bound_ctrl:1
	v_add_f32_dpp v126, v126, v127 quad_perm:[1,0,3,2] row_mask:0xf bank_mask:0xf bound_ctrl:1
	v_cndmask_b32_e64 v128, v124, v126, s[44:45]
	v_cndmask_b32_e64 v129, v126, v124, s[44:45]
	v_pk_mul_f32 v[136:137], v[24:25], v[60:61] op_sel_hi:[1,0]
	v_add_f32_dpp v130, v128, v129 quad_perm:[2,3,0,1] row_mask:0xf bank_mask:0xf bound_ctrl:1
	v_pk_mul_f32 v[138:139], v[26:27], v[60:61] op_sel_hi:[1,0]
	v_pk_mul_f32 v[140:141], v[24:25], v[60:61] op_sel:[0,1]
	v_add_f32_dpp v130, v130, v130 row_ror:4 row_mask:0xf bank_mask:0xf bound_ctrl:1
	v_pk_mul_f32 v[142:143], v[26:27], v[60:61] op_sel:[0,1]
	v_cndmask_b32_e64 v145, v61, v60, s[42:43]
	v_add_f32_dpp v130, v130, v130 row_ror:8 row_mask:0xf bank_mask:0xf bound_ctrl:1
	v_cndmask_b32_e32 v5, v5, v150, vcc
	s_nop 0
	v_mov_b32_dpp v132, v130 quad_perm:[0,0,0,0] row_mask:0xf bank_mask:0xf bound_ctrl:1
	v_mov_b32_dpp v134, v130 quad_perm:[1,1,1,1] row_mask:0xf bank_mask:0xf bound_ctrl:1
	v_pk_fma_f32 v[136:137], v[28:29], v[132:133], v[136:137] op_sel_hi:[1,0,1]
	v_pk_fma_f32 v[138:139], v[30:31], v[132:133], v[138:139] op_sel_hi:[1,0,1]
	v_pk_fma_f32 v[140:141], v[28:29], v[134:135], v[140:141] op_sel_hi:[1,0,1]
	v_pk_fma_f32 v[142:143], v[30:31], v[134:135], v[142:143] op_sel_hi:[1,0,1]
	v_cndmask_b32_e64 v144, v134, v132, s[42:43]
	v_pk_fma_f32 v[12:13], v[12:13], v[20:21], v[136:137]
	v_pk_fma_f32 v[14:15], v[14:15], v[22:23], v[138:139]
	v_fma_f32 v146, v145, v65, v130
	v_pk_fma_f32 v[16:17], v[16:17], v[20:21], v[140:141]
	v_pk_fma_f32 v[18:19], v[18:19], v[22:23], v[142:143]
	v_fmac_f32_e32 v146, v144, v64
	s_waitcnt lgkmcnt(0)
	ds_read_b128 v[32:35], v147 offset:40640
	ds_read_b128 v[36:39], v147 offset:40896
	ds_read_b128 v[24:27], v147 offset:40128
	ds_read_b64 v[60:61], v148 offset:41152
	ds_read_b128 v[28:31], v147 offset:40384
	ds_read_b128 v[20:23], v147 offset:39872
	ds_read_b64 v[64:65], v149 offset:41280
	v_mul_f32_e32 v120, v12, v52
	v_mul_f32_e32 v121, v16, v52
	v_mul_f32_e32 v122, v12, v56
	v_mul_f32_e32 v123, v16, v56
	v_fmac_f32_e32 v120, v13, v53
	v_fmac_f32_e32 v121, v17, v53
	v_fmac_f32_e32 v122, v13, v57
	v_fmac_f32_e32 v123, v17, v57
	v_fmac_f32_e32 v120, v14, v54
	v_fmac_f32_e32 v121, v18, v54
	v_fmac_f32_e32 v122, v14, v58
	v_fmac_f32_e32 v123, v18, v58
	v_fmac_f32_e32 v120, v15, v55
	v_fmac_f32_e32 v121, v19, v55
	v_fmac_f32_e32 v122, v15, v59
	v_fmac_f32_e32 v123, v19, v59
	v_cndmask_b32_e64 v124, v120, v121, s[42:43]
	v_cndmask_b32_e64 v126, v122, v123, s[42:43]
	v_cndmask_b32_e64 v125, v121, v120, s[42:43]
	v_cndmask_b32_e64 v127, v123, v122, s[42:43]
	v_add_f32_dpp v124, v124, v125 quad_perm:[1,0,3,2] row_mask:0xf bank_mask:0xf bound_ctrl:1
	v_add_f32_dpp v126, v126, v127 quad_perm:[1,0,3,2] row_mask:0xf bank_mask:0xf bound_ctrl:1
	v_cndmask_b32_e64 v128, v124, v126, s[44:45]
	v_cndmask_b32_e64 v129, v126, v124, s[44:45]
	v_pk_mul_f32 v[136:137], v[44:45], v[62:63] op_sel_hi:[1,0]
	v_add_f32_dpp v130, v128, v129 quad_perm:[2,3,0,1] row_mask:0xf bank_mask:0xf bound_ctrl:1
	v_pk_mul_f32 v[138:139], v[46:47], v[62:63] op_sel_hi:[1,0]
	v_pk_mul_f32 v[140:141], v[44:45], v[62:63] op_sel:[0,1]
	v_add_f32_dpp v130, v130, v130 row_ror:4 row_mask:0xf bank_mask:0xf bound_ctrl:1
	v_pk_mul_f32 v[142:143], v[46:47], v[62:63] op_sel:[0,1]
	v_cndmask_b32_e64 v145, v63, v62, s[42:43]
	v_add_f32_dpp v130, v130, v130 row_ror:8 row_mask:0xf bank_mask:0xf bound_ctrl:1
	v_cndmask_b32_e32 v6, v6, v146, vcc
	s_nop 0
	v_mov_b32_dpp v132, v130 quad_perm:[0,0,0,0] row_mask:0xf bank_mask:0xf bound_ctrl:1
	v_mov_b32_dpp v134, v130 quad_perm:[1,1,1,1] row_mask:0xf bank_mask:0xf bound_ctrl:1
	v_pk_fma_f32 v[136:137], v[48:49], v[132:133], v[136:137] op_sel_hi:[1,0,1]
	v_pk_fma_f32 v[138:139], v[50:51], v[132:133], v[138:139] op_sel_hi:[1,0,1]
	v_pk_fma_f32 v[140:141], v[48:49], v[134:135], v[140:141] op_sel_hi:[1,0,1]
	v_pk_fma_f32 v[142:143], v[50:51], v[134:135], v[142:143] op_sel_hi:[1,0,1]
	v_cndmask_b32_e64 v144, v134, v132, s[42:43]
	v_pk_fma_f32 v[12:13], v[12:13], v[40:41], v[136:137]
	v_pk_fma_f32 v[14:15], v[14:15], v[42:43], v[138:139]
	v_fma_f32 v150, v145, v67, v130
	v_pk_fma_f32 v[16:17], v[16:17], v[40:41], v[140:141]
	v_pk_fma_f32 v[18:19], v[18:19], v[42:43], v[142:143]
	v_fmac_f32_e32 v150, v144, v66
	s_waitcnt lgkmcnt(0)
	ds_read_b128 v[52:55], v147 offset:42064
	ds_read_b128 v[56:59], v147 offset:42320
	ds_read_b128 v[44:47], v147 offset:41552
	ds_read_b64 v[62:63], v148 offset:42576
	ds_read_b128 v[48:51], v147 offset:41808
	ds_read_b128 v[40:43], v147 offset:41296
	ds_read_b64 v[66:67], v149 offset:42704
	v_mul_f32_e32 v120, v12, v32
	v_mul_f32_e32 v121, v16, v32
	v_mul_f32_e32 v122, v12, v36
	v_mul_f32_e32 v123, v16, v36
	v_fmac_f32_e32 v120, v13, v33
	v_fmac_f32_e32 v121, v17, v33
	v_fmac_f32_e32 v122, v13, v37
	v_fmac_f32_e32 v123, v17, v37
	v_fmac_f32_e32 v120, v14, v34
	v_fmac_f32_e32 v121, v18, v34
	v_fmac_f32_e32 v122, v14, v38
	v_fmac_f32_e32 v123, v18, v38
	v_fmac_f32_e32 v120, v15, v35
	v_fmac_f32_e32 v121, v19, v35
	v_fmac_f32_e32 v122, v15, v39
	v_fmac_f32_e32 v123, v19, v39
	v_cndmask_b32_e64 v124, v120, v121, s[42:43]
	v_cndmask_b32_e64 v126, v122, v123, s[42:43]
	v_cndmask_b32_e64 v125, v121, v120, s[42:43]
	v_cndmask_b32_e64 v127, v123, v122, s[42:43]
	v_add_f32_dpp v124, v124, v125 quad_perm:[1,0,3,2] row_mask:0xf bank_mask:0xf bound_ctrl:1
	v_add_f32_dpp v126, v126, v127 quad_perm:[1,0,3,2] row_mask:0xf bank_mask:0xf bound_ctrl:1
	v_cndmask_b32_e64 v128, v124, v126, s[44:45]
	v_cndmask_b32_e64 v129, v126, v124, s[44:45]
	v_pk_mul_f32 v[136:137], v[24:25], v[60:61] op_sel_hi:[1,0]
	v_add_f32_dpp v130, v128, v129 quad_perm:[2,3,0,1] row_mask:0xf bank_mask:0xf bound_ctrl:1
	v_pk_mul_f32 v[138:139], v[26:27], v[60:61] op_sel_hi:[1,0]
	v_pk_mul_f32 v[140:141], v[24:25], v[60:61] op_sel:[0,1]
	v_add_f32_dpp v130, v130, v130 row_ror:4 row_mask:0xf bank_mask:0xf bound_ctrl:1
	v_pk_mul_f32 v[142:143], v[26:27], v[60:61] op_sel:[0,1]
	v_cndmask_b32_e64 v145, v61, v60, s[42:43]
	v_add_f32_dpp v130, v130, v130 row_ror:8 row_mask:0xf bank_mask:0xf bound_ctrl:1
	v_cndmask_b32_e32 v7, v7, v150, vcc
	v_cmp_eq_u32_e32 vcc, 3, v119
	v_mov_b32_dpp v132, v130 quad_perm:[0,0,0,0] row_mask:0xf bank_mask:0xf bound_ctrl:1
	v_mov_b32_dpp v134, v130 quad_perm:[1,1,1,1] row_mask:0xf bank_mask:0xf bound_ctrl:1
	v_pk_fma_f32 v[136:137], v[28:29], v[132:133], v[136:137] op_sel_hi:[1,0,1]
	v_pk_fma_f32 v[138:139], v[30:31], v[132:133], v[138:139] op_sel_hi:[1,0,1]
	v_pk_fma_f32 v[140:141], v[28:29], v[134:135], v[140:141] op_sel_hi:[1,0,1]
	v_pk_fma_f32 v[142:143], v[30:31], v[134:135], v[142:143] op_sel_hi:[1,0,1]
	v_cndmask_b32_e64 v144, v134, v132, s[42:43]
	v_pk_fma_f32 v[12:13], v[12:13], v[20:21], v[136:137]
	v_pk_fma_f32 v[14:15], v[14:15], v[22:23], v[138:139]
	v_fma_f32 v146, v145, v65, v130
	v_pk_fma_f32 v[16:17], v[16:17], v[20:21], v[140:141]
	v_pk_fma_f32 v[18:19], v[18:19], v[22:23], v[142:143]
	v_fmac_f32_e32 v146, v144, v64
	s_waitcnt lgkmcnt(0)
	ds_read_b128 v[32:35], v147 offset:43488
	ds_read_b128 v[36:39], v147 offset:43744
	ds_read_b128 v[24:27], v147 offset:42976
	ds_read_b64 v[60:61], v148 offset:44000
	ds_read_b128 v[28:31], v147 offset:43232
	ds_read_b128 v[20:23], v147 offset:42720
	ds_read_b64 v[64:65], v149 offset:44128
	v_mul_f32_e32 v120, v12, v52
	v_mul_f32_e32 v121, v16, v52
	v_mul_f32_e32 v122, v12, v56
	v_mul_f32_e32 v123, v16, v56
	v_fmac_f32_e32 v120, v13, v53
	v_fmac_f32_e32 v121, v17, v53
	v_fmac_f32_e32 v122, v13, v57
	v_fmac_f32_e32 v123, v17, v57
	v_fmac_f32_e32 v120, v14, v54
	v_fmac_f32_e32 v121, v18, v54
	v_fmac_f32_e32 v122, v14, v58
	v_fmac_f32_e32 v123, v18, v58
	v_fmac_f32_e32 v120, v15, v55
	v_fmac_f32_e32 v121, v19, v55
	v_fmac_f32_e32 v122, v15, v59
	v_fmac_f32_e32 v123, v19, v59
	v_cndmask_b32_e64 v124, v120, v121, s[42:43]
	v_cndmask_b32_e64 v126, v122, v123, s[42:43]
	v_cndmask_b32_e64 v125, v121, v120, s[42:43]
	v_cndmask_b32_e64 v127, v123, v122, s[42:43]
	v_add_f32_dpp v124, v124, v125 quad_perm:[1,0,3,2] row_mask:0xf bank_mask:0xf bound_ctrl:1
	v_add_f32_dpp v126, v126, v127 quad_perm:[1,0,3,2] row_mask:0xf bank_mask:0xf bound_ctrl:1
	v_cndmask_b32_e64 v128, v124, v126, s[44:45]
	v_cndmask_b32_e64 v129, v126, v124, s[44:45]
	v_pk_mul_f32 v[136:137], v[44:45], v[62:63] op_sel_hi:[1,0]
	v_add_f32_dpp v130, v128, v129 quad_perm:[2,3,0,1] row_mask:0xf bank_mask:0xf bound_ctrl:1
	v_pk_mul_f32 v[138:139], v[46:47], v[62:63] op_sel_hi:[1,0]
	v_pk_mul_f32 v[140:141], v[44:45], v[62:63] op_sel:[0,1]
	v_add_f32_dpp v130, v130, v130 row_ror:4 row_mask:0xf bank_mask:0xf bound_ctrl:1
	v_pk_mul_f32 v[142:143], v[46:47], v[62:63] op_sel:[0,1]
	v_cndmask_b32_e64 v145, v63, v62, s[42:43]
	v_add_f32_dpp v130, v130, v130 row_ror:8 row_mask:0xf bank_mask:0xf bound_ctrl:1
	v_cndmask_b32_e32 v4, v4, v146, vcc
	s_nop 0
	v_mov_b32_dpp v132, v130 quad_perm:[0,0,0,0] row_mask:0xf bank_mask:0xf bound_ctrl:1
	v_mov_b32_dpp v134, v130 quad_perm:[1,1,1,1] row_mask:0xf bank_mask:0xf bound_ctrl:1
	v_pk_fma_f32 v[136:137], v[48:49], v[132:133], v[136:137] op_sel_hi:[1,0,1]
	v_pk_fma_f32 v[138:139], v[50:51], v[132:133], v[138:139] op_sel_hi:[1,0,1]
	v_pk_fma_f32 v[140:141], v[48:49], v[134:135], v[140:141] op_sel_hi:[1,0,1]
	v_pk_fma_f32 v[142:143], v[50:51], v[134:135], v[142:143] op_sel_hi:[1,0,1]
	v_cndmask_b32_e64 v144, v134, v132, s[42:43]
	v_pk_fma_f32 v[12:13], v[12:13], v[40:41], v[136:137]
	v_pk_fma_f32 v[14:15], v[14:15], v[42:43], v[138:139]
	v_fma_f32 v150, v145, v67, v130
	v_pk_fma_f32 v[16:17], v[16:17], v[40:41], v[140:141]
	v_pk_fma_f32 v[18:19], v[18:19], v[42:43], v[142:143]
	v_fmac_f32_e32 v150, v144, v66
	s_waitcnt lgkmcnt(0)
	ds_read_b128 v[52:55], v147 offset:44912
	ds_read_b128 v[56:59], v147 offset:45168
	ds_read_b128 v[44:47], v147 offset:44400
	ds_read_b64 v[62:63], v148 offset:45424
	ds_read_b128 v[48:51], v147 offset:44656
	ds_read_b128 v[40:43], v147 offset:44144
	ds_read_b64 v[66:67], v149 offset:45552
	v_mul_f32_e32 v120, v12, v32
	v_mul_f32_e32 v121, v16, v32
	v_mul_f32_e32 v122, v12, v36
	v_mul_f32_e32 v123, v16, v36
	v_fmac_f32_e32 v120, v13, v33
	v_fmac_f32_e32 v121, v17, v33
	v_fmac_f32_e32 v122, v13, v37
	v_fmac_f32_e32 v123, v17, v37
	v_fmac_f32_e32 v120, v14, v34
	v_fmac_f32_e32 v121, v18, v34
	v_fmac_f32_e32 v122, v14, v38
	v_fmac_f32_e32 v123, v18, v38
	v_fmac_f32_e32 v120, v15, v35
	v_fmac_f32_e32 v121, v19, v35
	v_fmac_f32_e32 v122, v15, v39
	v_fmac_f32_e32 v123, v19, v39
	v_cndmask_b32_e64 v124, v120, v121, s[42:43]
	v_cndmask_b32_e64 v126, v122, v123, s[42:43]
	v_cndmask_b32_e64 v125, v121, v120, s[42:43]
	v_cndmask_b32_e64 v127, v123, v122, s[42:43]
	v_add_f32_dpp v124, v124, v125 quad_perm:[1,0,3,2] row_mask:0xf bank_mask:0xf bound_ctrl:1
	v_add_f32_dpp v126, v126, v127 quad_perm:[1,0,3,2] row_mask:0xf bank_mask:0xf bound_ctrl:1
	v_cndmask_b32_e64 v128, v124, v126, s[44:45]
	v_cndmask_b32_e64 v129, v126, v124, s[44:45]
	v_pk_mul_f32 v[136:137], v[24:25], v[60:61] op_sel_hi:[1,0]
	v_add_f32_dpp v130, v128, v129 quad_perm:[2,3,0,1] row_mask:0xf bank_mask:0xf bound_ctrl:1
	v_pk_mul_f32 v[138:139], v[26:27], v[60:61] op_sel_hi:[1,0]
	v_pk_mul_f32 v[140:141], v[24:25], v[60:61] op_sel:[0,1]
	v_add_f32_dpp v130, v130, v130 row_ror:4 row_mask:0xf bank_mask:0xf bound_ctrl:1
	v_pk_mul_f32 v[142:143], v[26:27], v[60:61] op_sel:[0,1]
	v_cndmask_b32_e64 v145, v61, v60, s[42:43]
	v_add_f32_dpp v130, v130, v130 row_ror:8 row_mask:0xf bank_mask:0xf bound_ctrl:1
	v_cndmask_b32_e32 v5, v5, v150, vcc
	s_nop 0
	v_mov_b32_dpp v132, v130 quad_perm:[0,0,0,0] row_mask:0xf bank_mask:0xf bound_ctrl:1
	v_mov_b32_dpp v134, v130 quad_perm:[1,1,1,1] row_mask:0xf bank_mask:0xf bound_ctrl:1
	v_pk_fma_f32 v[136:137], v[28:29], v[132:133], v[136:137] op_sel_hi:[1,0,1]
	v_pk_fma_f32 v[138:139], v[30:31], v[132:133], v[138:139] op_sel_hi:[1,0,1]
	v_pk_fma_f32 v[140:141], v[28:29], v[134:135], v[140:141] op_sel_hi:[1,0,1]
	v_pk_fma_f32 v[142:143], v[30:31], v[134:135], v[142:143] op_sel_hi:[1,0,1]
	v_cndmask_b32_e64 v144, v134, v132, s[42:43]
	v_pk_fma_f32 v[12:13], v[12:13], v[20:21], v[136:137]
	v_pk_fma_f32 v[14:15], v[14:15], v[22:23], v[138:139]
	v_fma_f32 v146, v145, v65, v130
	v_pk_fma_f32 v[16:17], v[16:17], v[20:21], v[140:141]
	v_pk_fma_f32 v[18:19], v[18:19], v[22:23], v[142:143]
	v_fmac_f32_e32 v146, v144, v64
	s_waitcnt lgkmcnt(0)
	v_mul_f32_e32 v120, v12, v52
	v_mul_f32_e32 v121, v16, v52
	v_mul_f32_e32 v122, v12, v56
	v_mul_f32_e32 v123, v16, v56
	v_fmac_f32_e32 v120, v13, v53
	v_fmac_f32_e32 v121, v17, v53
	v_fmac_f32_e32 v122, v13, v57
	v_fmac_f32_e32 v123, v17, v57
	v_fmac_f32_e32 v120, v14, v54
	v_fmac_f32_e32 v121, v18, v54
	v_fmac_f32_e32 v122, v14, v58
	v_fmac_f32_e32 v123, v18, v58
	v_fmac_f32_e32 v120, v15, v55
	v_fmac_f32_e32 v121, v19, v55
	v_fmac_f32_e32 v122, v15, v59
	v_fmac_f32_e32 v123, v19, v59
	v_cndmask_b32_e64 v124, v120, v121, s[42:43]
	v_cndmask_b32_e64 v126, v122, v123, s[42:43]
	v_cndmask_b32_e64 v125, v121, v120, s[42:43]
	v_cndmask_b32_e64 v127, v123, v122, s[42:43]
	v_add_f32_dpp v124, v124, v125 quad_perm:[1,0,3,2] row_mask:0xf bank_mask:0xf bound_ctrl:1
	v_add_f32_dpp v126, v126, v127 quad_perm:[1,0,3,2] row_mask:0xf bank_mask:0xf bound_ctrl:1
	v_cndmask_b32_e64 v128, v124, v126, s[44:45]
	v_cndmask_b32_e64 v129, v126, v124, s[44:45]
	v_pk_mul_f32 v[136:137], v[44:45], v[62:63] op_sel_hi:[1,0]
	v_add_f32_dpp v130, v128, v129 quad_perm:[2,3,0,1] row_mask:0xf bank_mask:0xf bound_ctrl:1
	v_pk_mul_f32 v[138:139], v[46:47], v[62:63] op_sel_hi:[1,0]
	v_pk_mul_f32 v[140:141], v[44:45], v[62:63] op_sel:[0,1]
	v_add_f32_dpp v130, v130, v130 row_ror:4 row_mask:0xf bank_mask:0xf bound_ctrl:1
	v_pk_mul_f32 v[142:143], v[46:47], v[62:63] op_sel:[0,1]
	v_cndmask_b32_e64 v145, v63, v62, s[42:43]
	v_add_f32_dpp v130, v130, v130 row_ror:8 row_mask:0xf bank_mask:0xf bound_ctrl:1
	v_cndmask_b32_e32 v6, v6, v146, vcc
	s_nop 0
	v_mov_b32_dpp v132, v130 quad_perm:[0,0,0,0] row_mask:0xf bank_mask:0xf bound_ctrl:1
	v_mov_b32_dpp v134, v130 quad_perm:[1,1,1,1] row_mask:0xf bank_mask:0xf bound_ctrl:1
	v_pk_fma_f32 v[136:137], v[48:49], v[132:133], v[136:137] op_sel_hi:[1,0,1]
	v_pk_fma_f32 v[138:139], v[50:51], v[132:133], v[138:139] op_sel_hi:[1,0,1]
	v_pk_fma_f32 v[140:141], v[48:49], v[134:135], v[140:141] op_sel_hi:[1,0,1]
	v_pk_fma_f32 v[142:143], v[50:51], v[134:135], v[142:143] op_sel_hi:[1,0,1]
	v_cndmask_b32_e64 v144, v134, v132, s[42:43]
	v_pk_fma_f32 v[12:13], v[12:13], v[40:41], v[136:137]
	v_pk_fma_f32 v[14:15], v[14:15], v[42:43], v[138:139]
	v_fma_f32 v150, v145, v67, v130
	v_pk_fma_f32 v[16:17], v[16:17], v[40:41], v[140:141]
	v_pk_fma_f32 v[18:19], v[18:19], v[42:43], v[142:143]
	v_fmac_f32_e32 v150, v144, v66
	s_nop 0
	v_cndmask_b32_e32 v7, v7, v150, vcc
	s_and_saveexec_b64 s[78:79], s[46:47]
	s_cbranch_execz .LBB0_458
	s_waitcnt lgkmcnt(8)
	v_lshl_add_u32 v20, s22, 12, v115
	ds_write2_b32 v20, v0, v1 offset1:32
	ds_write2_b32 v20, v2, v3 offset0:64 offset1:96
	v_add_u32_e32 v0, 0x800, v20
	ds_write2_b32 v0, v4, v5 offset1:32
	ds_write2_b32 v0, v6, v7 offset0:64 offset1:96
